# v24 plus nt policy on the bf16 weight-copy stores of the conversion phase
# speedup vs baseline: 1.0118x; 1.0042x over previous
; __device__ __forceinline__ void cvt_item(gfp W, int N, bf16* WT, int Kd, int k0, int n0, int drow0, LAS float* scr, int lane, gfp gk) {
; #pragma unroll 8
;     for (int i = 0; i < 32; ++i) { const int kk = 2 * i + (lane >> 5); scr[kk * 33 + (lane & 31)] = W[(size_t)(k0 + kk) * N + n0 + (lane & 31)]; }
.LBB0_123:
	v_mov_b32_e32 v103, v1
	s_lshl_b32 s30, s25, 1
	s_lshl_b32 s27, s23, 1
	v_or_b32_e32 v136, s30, v10
	s_add_i32 s33, s30, 4
	s_add_i32 s31, s27, 4
	s_add_i32 s34, s27, 8
	s_add_i32 s35, s30, 8
	v_add_u32_e32 v102, s0, v136
	v_or_b32_e32 v127, s33, v10
	v_or_b32_e32 v101, s27, v11
	s_add_i32 s36, s27, 12
	s_add_i32 s37, s30, 12
	s_add_i32 s38, s27, 16
	s_add_i32 s40, s27, 20
	s_add_i32 s42, s27, 24
	s_add_i32 s27, s27, 28
	v_or_b32_e32 v126, s31, v11
	v_or_b32_e32 v128, s34, v11
	v_or_b32_e32 v129, s35, v10
	v_lshlrev_b64 v[120:121], 13, v[102:103]
	v_add_u32_e32 v102, s0, v127
	v_mov_b32_e32 v105, v103
	v_mov_b32_e32 v107, v103
	v_mov_b32_e32 v109, v103
	s_add_i32 s39, s30, 16
	v_add_u32_e32 v104, s22, v101
	v_or_b32_e32 v130, s36, v11
	v_or_b32_e32 v131, s37, v10
	v_or_b32_e32 v132, s38, v11
	v_or_b32_e32 v134, s40, v11
	v_or_b32_e32 v137, s42, v11
	v_or_b32_e32 v139, s27, v11
	v_add_u32_e32 v106, s22, v126
	v_add_u32_e32 v108, s22, v128
	v_lshlrev_b64 v[122:123], 13, v[102:103]
	v_add_u32_e32 v102, s0, v129
	v_mov_b32_e32 v111, v103
	v_mov_b32_e32 v113, v103
	v_mov_b32_e32 v115, v103
	v_mov_b32_e32 v117, v103
	v_mov_b32_e32 v119, v103
	s_add_i32 s41, s30, 20
	v_or_b32_e32 v133, s39, v10
	v_lshlrev_b64 v[104:105], 13, v[104:105]
	v_add_u32_e32 v110, s22, v130
	v_add_u32_e32 v112, s22, v132
	v_add_u32_e32 v114, s22, v134
	v_add_u32_e32 v116, s22, v137
	v_add_u32_e32 v118, s22, v139
	v_lshl_add_u64 v[120:121], v[2:3], 0, v[120:121]
	v_lshlrev_b64 v[106:107], 13, v[106:107]
	v_lshlrev_b64 v[108:109], 13, v[108:109]
	v_lshlrev_b64 v[124:125], 13, v[102:103]
	v_add_u32_e32 v102, s0, v131
	s_add_i32 s43, s30, 24
	v_or_b32_e32 v135, s41, v10
	v_lshl_add_u64 v[104:105], v[2:3], 0, v[104:105]
	v_lshlrev_b64 v[110:111], 13, v[110:111]
	v_lshlrev_b64 v[112:113], 13, v[112:113]
	v_lshlrev_b64 v[114:115], 13, v[114:115]
	v_lshlrev_b64 v[116:117], 13, v[116:117]
	v_lshlrev_b64 v[118:119], 13, v[118:119]
	v_lshl_add_u64 v[122:123], v[2:3], 0, v[122:123]
	v_lshl_add_u64 v[106:107], v[2:3], 0, v[106:107]
	v_lshl_add_u64 v[108:109], v[2:3], 0, v[108:109]
	global_load_dword v141, v[120:121], off nt
	global_load_dword v142, v[104:105], off nt
	v_lshlrev_b64 v[120:121], 13, v[102:103]
	v_add_u32_e32 v102, s0, v133
	s_add_i32 s30, s30, 28
	v_or_b32_e32 v138, s43, v10
	v_lshl_add_u64 v[110:111], v[2:3], 0, v[110:111]
	v_lshl_add_u64 v[112:113], v[2:3], 0, v[112:113]
	v_lshl_add_u64 v[114:115], v[2:3], 0, v[114:115]
	v_lshl_add_u64 v[116:117], v[2:3], 0, v[116:117]
	v_lshl_add_u64 v[118:119], v[2:3], 0, v[118:119]
	global_load_dword v143, v[122:123], off nt
	global_load_dword v144, v[106:107], off nt
	global_load_dword v145, v[108:109], off nt
	global_load_dword v146, v[110:111], off nt
	global_load_dword v147, v[112:113], off nt
	global_load_dword v148, v[114:115], off nt
	global_load_dword v149, v[116:117], off nt
	global_load_dword v150, v[118:119], off nt
	v_lshl_add_u64 v[106:107], v[2:3], 0, v[120:121]
	v_lshlrev_b64 v[108:109], 13, v[102:103]
	v_add_u32_e32 v102, s0, v135
	v_or_b32_e32 v140, s30, v10
	v_lshl_add_u64 v[104:105], v[2:3], 0, v[124:125]
	global_load_dword v151, v[106:107], off nt
	global_load_dword v152, v[104:105], off nt
	v_lshlrev_b64 v[106:107], 13, v[102:103]
	v_add_u32_e32 v102, s0, v138
	v_lshl_add_u64 v[104:105], v[2:3], 0, v[108:109]
	v_lshlrev_b64 v[108:109], 13, v[102:103]
	v_add_u32_e32 v102, s0, v140
	v_lshlrev_b64 v[110:111], 13, v[102:103]
	v_lshl_add_u64 v[110:111], v[2:3], 0, v[110:111]
	v_lshl_add_u64 v[106:107], v[2:3], 0, v[106:107]
	v_lshl_add_u64 v[108:109], v[2:3], 0, v[108:109]
	global_load_dword v102, v[110:111], off nt
	global_load_dword v153, v[108:109], off nt
	global_load_dword v154, v[106:107], off nt
	global_load_dword v155, v[104:105], off nt
	s_add_i32 s25, s25, 16
	s_add_i32 s23, s23, 16
	s_add_i32 s26, s26, -16
	s_cmp_lg_u32 s26, 0
	s_lshl_b32 s30, s25, 1
	s_lshl_b32 s27, s23, 1
	v_or_b32_e32 v45, s30, v10
	s_add_i32 s33, s30, 4
	s_add_i32 s31, s27, 4
	s_add_i32 s34, s27, 8
	s_add_i32 s35, s30, 8
	v_add_u32_e32 v0, s0, v45
	v_or_b32_e32 v63, s33, v10
	v_or_b32_e32 v39, s27, v11
	s_add_i32 s36, s27, 12
	s_add_i32 s37, s30, 12
	s_add_i32 s38, s27, 16
	s_add_i32 s40, s27, 20
	s_add_i32 s42, s27, 24
	s_add_i32 s27, s27, 28
	v_or_b32_e32 v62, s31, v11
	v_or_b32_e32 v64, s34, v11
	v_or_b32_e32 v65, s35, v10
	v_lshlrev_b64 v[56:57], 13, v[0:1]
	v_add_u32_e32 v0, s0, v63
	v_mov_b32_e32 v5, v1
	v_mov_b32_e32 v7, v1
	v_mov_b32_e32 v9, v1
	s_add_i32 s39, s30, 16
	v_add_u32_e32 v4, s22, v39
	v_or_b32_e32 v66, s36, v11
	v_or_b32_e32 v67, s37, v10
	v_or_b32_e32 v68, s38, v11
	v_or_b32_e32 v70, s40, v11
	v_or_b32_e32 v72, s42, v11
	v_or_b32_e32 v74, s27, v11
	v_add_u32_e32 v6, s22, v62
	v_add_u32_e32 v8, s22, v64
	v_lshlrev_b64 v[58:59], 13, v[0:1]
	v_add_u32_e32 v0, s0, v65
	v_mov_b32_e32 v47, v1
	v_mov_b32_e32 v49, v1
	v_mov_b32_e32 v51, v1
	v_mov_b32_e32 v53, v1
	v_mov_b32_e32 v55, v1
	s_add_i32 s41, s30, 20
	v_or_b32_e32 v69, s39, v10
	v_lshlrev_b64 v[4:5], 13, v[4:5]
	v_add_u32_e32 v46, s22, v66
	v_add_u32_e32 v48, s22, v68
	v_add_u32_e32 v50, s22, v70
	v_add_u32_e32 v52, s22, v72
	v_add_u32_e32 v54, s22, v74
	v_lshl_add_u64 v[56:57], v[2:3], 0, v[56:57]
	v_lshlrev_b64 v[6:7], 13, v[6:7]
	v_lshlrev_b64 v[8:9], 13, v[8:9]
	v_lshlrev_b64 v[60:61], 13, v[0:1]
	v_add_u32_e32 v0, s0, v67
	s_add_i32 s43, s30, 24
	v_or_b32_e32 v71, s41, v10
	v_lshl_add_u64 v[4:5], v[2:3], 0, v[4:5]
	v_lshlrev_b64 v[46:47], 13, v[46:47]
	v_lshlrev_b64 v[48:49], 13, v[48:49]
	v_lshlrev_b64 v[50:51], 13, v[50:51]
	v_lshlrev_b64 v[52:53], 13, v[52:53]
	v_lshlrev_b64 v[54:55], 13, v[54:55]
	v_lshl_add_u64 v[58:59], v[2:3], 0, v[58:59]
; #define GAS __attribute__((address_space(1)))
; #define LAS __attribute__((address_space(3)))
; #define LDS_WAIT() asm volatile("s_waitcnt lgkmcnt(0)" ::: "memory")
; __device__ __forceinline__ unsigned pk2(float lo, float hi) { unsigned r; asm("v_cvt_pk_bf16_f32 %0, %1, %2" : "=v"(r) : "v"(lo), "v"(hi)); return r; }
; __device__ __forceinline__ void cvt_item(gfp W, int N, bf16* WT, int Kd, int k0, int n0, int drow0, LAS float* scr, int lane, gfp gk) {
; #pragma unroll 8
;     for (int i = 0; i < 32; ++i) { const int kk = 2 * i + (lane >> 5); scr[kk * 33 + (lane & 31)] = W[(size_t)(k0 + kk) * N + n0 + (lane & 31)]; }
;     const int c = lane & 7;
;     f32x4 ga = (f32x4){1.f, 1.f, 1.f, 1.f}, gb = ga;
;     if (gk != nullptr) { ga = *(const GAS f32x4*)(gk + k0 + 8 * c); gb = *(const GAS f32x4*)(gk + k0 + 8 * c + 4); }
;     LDS_WAIT(); asm volatile("" ::: "memory");
; #pragma unroll
;     for (int j = 0; j < 4; ++j) { const int n = (lane >> 3) + 8 * j; const LAS float* s = scr + (8 * c) * 33 + n;
;         v4u o; o.x = pk2(s[0 * 33] * ga[0], s[1 * 33] * ga[1]); o.y = pk2(s[2 * 33] * ga[2], s[3 * 33] * ga[3]); o.z = pk2(s[4 * 33] * gb[0], s[5 * 33] * gb[1]); o.w = pk2(s[6 * 33] * gb[2], s[7 * 33] * gb[3]);
;         *(GAS v4u*)(WT + (size_t)(drow0 + n) * Kd + k0 + 8 * c) = o; }
;     LDS_WAIT(); asm volatile("" ::: "memory");
	v_lshl_add_u64 v[6:7], v[2:3], 0, v[6:7]
	v_lshl_add_u64 v[8:9], v[2:3], 0, v[8:9]
	global_load_dword v76, v[56:57], off nt
	global_load_dword v77, v[4:5], off nt
	v_lshlrev_b64 v[56:57], 13, v[0:1]
	v_add_u32_e32 v0, s0, v69
	s_add_i32 s30, s30, 28
	v_or_b32_e32 v73, s43, v10
	v_lshl_add_u64 v[46:47], v[2:3], 0, v[46:47]
	v_lshl_add_u64 v[48:49], v[2:3], 0, v[48:49]
	v_lshl_add_u64 v[50:51], v[2:3], 0, v[50:51]
	v_lshl_add_u64 v[52:53], v[2:3], 0, v[52:53]
	v_lshl_add_u64 v[54:55], v[2:3], 0, v[54:55]
	global_load_dword v78, v[58:59], off nt
	global_load_dword v79, v[6:7], off nt
	global_load_dword v80, v[8:9], off nt
	global_load_dword v81, v[46:47], off nt
	global_load_dword v82, v[48:49], off nt
	global_load_dword v83, v[50:51], off nt
	global_load_dword v84, v[52:53], off nt
	global_load_dword v85, v[54:55], off nt
	v_lshl_add_u64 v[6:7], v[2:3], 0, v[56:57]
	v_lshlrev_b64 v[8:9], 13, v[0:1]
	v_add_u32_e32 v0, s0, v71
	v_or_b32_e32 v75, s30, v10
	v_lshl_add_u64 v[4:5], v[2:3], 0, v[60:61]
	global_load_dword v86, v[6:7], off nt
	global_load_dword v87, v[4:5], off nt
	v_lshlrev_b64 v[6:7], 13, v[0:1]
	v_add_u32_e32 v0, s0, v73
	v_lshl_add_u64 v[4:5], v[2:3], 0, v[8:9]
	v_lshlrev_b64 v[8:9], 13, v[0:1]
	v_add_u32_e32 v0, s0, v75
	v_lshlrev_b64 v[46:47], 13, v[0:1]
	v_lshl_add_u64 v[46:47], v[2:3], 0, v[46:47]
	v_lshl_add_u64 v[6:7], v[2:3], 0, v[6:7]
	v_lshl_add_u64 v[8:9], v[2:3], 0, v[8:9]
	global_load_dword v0, v[46:47], off nt
	global_load_dword v88, v[8:9], off nt
	global_load_dword v89, v[6:7], off nt
	global_load_dword v90, v[4:5], off nt
	v_mad_u64_u32 v[104:105], s[30:31], v136, s81, v[12:13]
	v_mad_u64_u32 v[106:107], s[30:31], v101, s81, v[12:13]
	v_mad_u64_u32 v[108:109], s[30:31], v127, s81, v[12:13]
	v_mad_u64_u32 v[110:111], s[30:31], v126, s81, v[12:13]
	v_mad_u64_u32 v[112:113], s[30:31], v129, s81, v[12:13]
	v_mad_u64_u32 v[114:115], s[30:31], v128, s81, v[12:13]
	v_mad_u64_u32 v[116:117], s[30:31], v131, s81, v[12:13]
	v_mad_u64_u32 v[118:119], s[30:31], v130, s81, v[12:13]
	v_mad_u64_u32 v[120:121], s[30:31], v133, s81, v[12:13]
	v_mad_u64_u32 v[122:123], s[30:31], v132, s81, v[12:13]
	v_mad_u64_u32 v[124:125], s[30:31], v135, s81, v[12:13]
	v_mad_u64_u32 v[126:127], s[30:31], v134, s81, v[12:13]
	v_mad_u64_u32 v[128:129], s[30:31], v138, s81, v[12:13]
	v_mad_u64_u32 v[130:131], s[30:31], v137, s81, v[12:13]
	v_mad_u64_u32 v[132:133], s[30:31], v140, s81, v[12:13]
	v_mad_u64_u32 v[134:135], s[30:31], v139, s81, v[12:13]
	s_waitcnt vmcnt(31)
	ds_write_b32 v104, v141
	s_waitcnt vmcnt(30)
	ds_write_b32 v106, v142
	s_waitcnt vmcnt(29)
	ds_write_b32 v108, v143
	s_waitcnt vmcnt(28)
	ds_write_b32 v110, v144
	s_waitcnt vmcnt(20)
	ds_write_b32 v112, v152
	ds_write_b32 v114, v145
	ds_write_b32 v116, v151
	ds_write_b32 v118, v146
	s_waitcnt vmcnt(16)
	ds_write_b32 v120, v155
	ds_write_b32 v122, v147
	ds_write_b32 v124, v154
	ds_write_b32 v126, v148
	ds_write_b32 v128, v153
	ds_write_b32 v130, v149
	ds_write_b32 v132, v102
	ds_write_b32 v134, v150
	v_mad_u64_u32 v[4:5], s[30:31], v45, s81, v[12:13]
	v_mad_u64_u32 v[6:7], s[30:31], v39, s81, v[12:13]
	v_mad_u64_u32 v[8:9], s[30:31], v63, s81, v[12:13]
	v_mad_u64_u32 v[46:47], s[30:31], v62, s81, v[12:13]
	v_mad_u64_u32 v[48:49], s[30:31], v65, s81, v[12:13]
	v_mad_u64_u32 v[50:51], s[30:31], v64, s81, v[12:13]
	v_mad_u64_u32 v[52:53], s[30:31], v67, s81, v[12:13]
	v_mad_u64_u32 v[54:55], s[30:31], v66, s81, v[12:13]
	v_mad_u64_u32 v[56:57], s[30:31], v69, s81, v[12:13]
	v_mad_u64_u32 v[58:59], s[30:31], v68, s81, v[12:13]
	v_mad_u64_u32 v[60:61], s[30:31], v71, s81, v[12:13]
	v_mad_u64_u32 v[62:63], s[30:31], v70, s81, v[12:13]
	v_mad_u64_u32 v[64:65], s[30:31], v73, s81, v[12:13]
	v_mad_u64_u32 v[66:67], s[30:31], v72, s81, v[12:13]
	v_mad_u64_u32 v[68:69], s[30:31], v75, s81, v[12:13]
	v_mad_u64_u32 v[70:71], s[30:31], v74, s81, v[12:13]
	s_waitcnt vmcnt(15)
	ds_write_b32 v4, v76
	s_waitcnt vmcnt(14)
	ds_write_b32 v6, v77
	s_waitcnt vmcnt(13)
	ds_write_b32 v8, v78
	s_waitcnt vmcnt(12)
	ds_write_b32 v46, v79
	s_waitcnt vmcnt(4)
	ds_write_b32 v48, v87
	ds_write_b32 v50, v80
	ds_write_b32 v52, v86
	ds_write_b32 v54, v81
	s_waitcnt vmcnt(0)
	ds_write_b32 v56, v90
	ds_write_b32 v58, v82
	ds_write_b32 v60, v89
	ds_write_b32 v62, v83
	ds_write_b32 v64, v88
	ds_write_b32 v66, v84
	ds_write_b32 v68, v0
	ds_write_b32 v70, v85
	s_add_i32 s25, s25, 16
	s_add_i32 s23, s23, 16
	s_add_i32 s26, s26, -16
	s_cmp_lg_u32 s26, 0
	s_waitcnt lgkmcnt(0)
	ds_read2_b32 v[6:7], v41 offset0:33 offset1:41
	ds_read2_b32 v[8:9], v41 offset1:8
	ds_read2_b32 v[46:47], v41 offset0:66 offset1:74
	ds_read2_b32 v[48:49], v41 offset0:99 offset1:107
	ds_read2_b32 v[50:51], v41 offset0:132 offset1:140
	ds_read2_b32 v[52:53], v41 offset0:165 offset1:173
	ds_read2_b32 v[54:55], v41 offset0:198 offset1:206
	ds_read2_b32 v[56:57], v41 offset0:231 offset1:239
	s_lshl_b32 s0, s0, 1
	v_or_b32_e32 v0, s24, v40
	v_lshl_add_u64 v[58:59], v[16:17], 0, s[0:1]
	v_lshlrev_b32_e32 v0, 12, v0
	v_lshl_add_u64 v[60:61], v[58:59], 0, v[0:1]
	s_waitcnt lgkmcnt(6)
	v_cvt_pk_bf16_f32 v2, v8, v6
	s_waitcnt lgkmcnt(4)
	v_cvt_pk_bf16_f32 v3, v46, v48
	s_waitcnt lgkmcnt(2)
	v_cvt_pk_bf16_f32 v4, v50, v52
	s_waitcnt lgkmcnt(0)
	v_cvt_pk_bf16_f32 v5, v54, v56
	global_store_dwordx4 v[60:61], v[2:5], off nt
	v_or_b32_e32 v0, s24, v42
	v_lshlrev_b32_e32 v0, 12, v0
	v_cvt_pk_bf16_f32 v2, v9, v7
	v_cvt_pk_bf16_f32 v3, v47, v49
	v_cvt_pk_bf16_f32 v4, v51, v53
	v_cvt_pk_bf16_f32 v5, v55, v57
	ds_read2_b32 v[8:9], v41 offset0:16 offset1:24
	ds_read2_b32 v[46:47], v41 offset0:49 offset1:57
	ds_read2_b32 v[48:49], v41 offset0:82 offset1:90
	ds_read2_b32 v[50:51], v41 offset0:115 offset1:123
	ds_read2_b32 v[52:53], v41 offset0:148 offset1:156
	ds_read2_b32 v[54:55], v41 offset0:181 offset1:189
	ds_read2_b32 v[56:57], v41 offset0:214 offset1:222
	ds_read2_b32 v[60:61], v41 offset0:247 offset1:255
	v_lshl_add_u64 v[6:7], v[58:59], 0, v[0:1]
	v_or_b32_e32 v0, s24, v43
	v_lshlrev_b32_e32 v0, 12, v0
	global_store_dwordx4 v[6:7], v[2:5], off nt
	v_lshl_add_u64 v[6:7], v[58:59], 0, v[0:1]
	v_or_b32_e32 v0, s24, v44
	v_lshlrev_b32_e32 v0, 12, v0
	s_waitcnt lgkmcnt(6)
	v_cvt_pk_bf16_f32 v2, v8, v46
	s_waitcnt lgkmcnt(4)
	v_cvt_pk_bf16_f32 v3, v48, v50
	s_waitcnt lgkmcnt(2)
	v_cvt_pk_bf16_f32 v4, v52, v54
	s_waitcnt lgkmcnt(0)
	v_cvt_pk_bf16_f32 v5, v56, v60
	global_store_dwordx4 v[6:7], v[2:5], off nt
	v_lshl_add_u64 v[6:7], v[58:59], 0, v[0:1]
	s_mov_b64 s[22:23], 0
	v_cvt_pk_bf16_f32 v2, v9, v47
	v_cvt_pk_bf16_f32 v3, v49, v51
	v_cvt_pk_bf16_f32 v4, v53, v55
	v_cvt_pk_bf16_f32 v5, v57, v61
	global_store_dwordx4 v[6:7], v[2:5], off nt
	s_waitcnt lgkmcnt(0)

; __device__ __forceinline__ void cvt_item(gfp W, int N, bf16* WT, int Kd, int k0, int n0, int drow0, LAS float* scr, int lane, gfp gk) {
; #pragma unroll 8
;     for (int i = 0; i < 32; ++i) { const int kk = 2 * i + (lane >> 5); scr[kk * 33 + (lane & 31)] = W[(size_t)(k0 + kk) * N + n0 + (lane & 31)]; }
.LBB0_127:
	v_mov_b32_e32 v103, v1
	s_lshl_b32 s30, s25, 1
	s_lshl_b32 s27, s23, 1
	v_or_b32_e32 v136, s30, v10
	s_add_i32 s33, s30, 4
	s_add_i32 s31, s27, 4
	s_add_i32 s34, s27, 8
	s_add_i32 s35, s30, 8
	v_add_u32_e32 v102, s0, v136
	v_or_b32_e32 v127, s33, v10
	v_or_b32_e32 v101, s27, v11
	s_add_i32 s36, s27, 12
	s_add_i32 s37, s30, 12
	s_add_i32 s38, s27, 16
	s_add_i32 s40, s27, 20
	s_add_i32 s42, s27, 24
	s_add_i32 s27, s27, 28
	v_or_b32_e32 v126, s31, v11
	v_or_b32_e32 v128, s34, v11
	v_or_b32_e32 v129, s35, v10
	v_lshlrev_b64 v[120:121], 13, v[102:103]
	v_add_u32_e32 v102, s0, v127
	v_mov_b32_e32 v105, v103
	v_mov_b32_e32 v107, v103
	v_mov_b32_e32 v109, v103
	s_add_i32 s39, s30, 16
	v_add_u32_e32 v104, s22, v101
	v_or_b32_e32 v130, s36, v11
	v_or_b32_e32 v131, s37, v10
	v_or_b32_e32 v132, s38, v11
	v_or_b32_e32 v134, s40, v11
	v_or_b32_e32 v137, s42, v11
	v_or_b32_e32 v139, s27, v11
	v_add_u32_e32 v106, s22, v126
	v_add_u32_e32 v108, s22, v128
	v_lshlrev_b64 v[122:123], 13, v[102:103]
	v_add_u32_e32 v102, s0, v129
	v_mov_b32_e32 v111, v103
	v_mov_b32_e32 v113, v103
	v_mov_b32_e32 v115, v103
	v_mov_b32_e32 v117, v103
	v_mov_b32_e32 v119, v103
	s_add_i32 s41, s30, 20
	v_or_b32_e32 v133, s39, v10
	v_lshlrev_b64 v[104:105], 13, v[104:105]
	v_add_u32_e32 v110, s22, v130
	v_add_u32_e32 v112, s22, v132
	v_add_u32_e32 v114, s22, v134
	v_add_u32_e32 v116, s22, v137
	v_add_u32_e32 v118, s22, v139
	v_lshl_add_u64 v[120:121], v[2:3], 0, v[120:121]
	v_lshlrev_b64 v[106:107], 13, v[106:107]
	v_lshlrev_b64 v[108:109], 13, v[108:109]
	v_lshlrev_b64 v[124:125], 13, v[102:103]
	v_add_u32_e32 v102, s0, v131
	s_add_i32 s43, s30, 24
	v_or_b32_e32 v135, s41, v10
	v_lshl_add_u64 v[104:105], v[2:3], 0, v[104:105]
	v_lshlrev_b64 v[110:111], 13, v[110:111]
	v_lshlrev_b64 v[112:113], 13, v[112:113]
	v_lshlrev_b64 v[114:115], 13, v[114:115]
	v_lshlrev_b64 v[116:117], 13, v[116:117]
	v_lshlrev_b64 v[118:119], 13, v[118:119]
	v_lshl_add_u64 v[122:123], v[2:3], 0, v[122:123]
	v_lshl_add_u64 v[106:107], v[2:3], 0, v[106:107]
	v_lshl_add_u64 v[108:109], v[2:3], 0, v[108:109]
	global_load_dword v141, v[120:121], off nt
	global_load_dword v142, v[104:105], off nt
	v_lshlrev_b64 v[120:121], 13, v[102:103]
	v_add_u32_e32 v102, s0, v133
	s_add_i32 s30, s30, 28
	v_or_b32_e32 v138, s43, v10
	v_lshl_add_u64 v[110:111], v[2:3], 0, v[110:111]
	v_lshl_add_u64 v[112:113], v[2:3], 0, v[112:113]
	v_lshl_add_u64 v[114:115], v[2:3], 0, v[114:115]
	v_lshl_add_u64 v[116:117], v[2:3], 0, v[116:117]
	v_lshl_add_u64 v[118:119], v[2:3], 0, v[118:119]
	global_load_dword v143, v[122:123], off nt
	global_load_dword v144, v[106:107], off nt
	global_load_dword v145, v[108:109], off nt
	global_load_dword v146, v[110:111], off nt
	global_load_dword v147, v[112:113], off nt
	global_load_dword v148, v[114:115], off nt
	global_load_dword v149, v[116:117], off nt
	global_load_dword v150, v[118:119], off nt
	v_lshl_add_u64 v[106:107], v[2:3], 0, v[120:121]
	v_lshlrev_b64 v[108:109], 13, v[102:103]
	v_add_u32_e32 v102, s0, v135
	v_or_b32_e32 v140, s30, v10
	v_lshl_add_u64 v[104:105], v[2:3], 0, v[124:125]
	global_load_dword v151, v[106:107], off nt
	global_load_dword v152, v[104:105], off nt
	v_lshlrev_b64 v[106:107], 13, v[102:103]
	v_add_u32_e32 v102, s0, v138
	v_lshl_add_u64 v[104:105], v[2:3], 0, v[108:109]
	v_lshlrev_b64 v[108:109], 13, v[102:103]
	v_add_u32_e32 v102, s0, v140
	v_lshlrev_b64 v[110:111], 13, v[102:103]
	v_lshl_add_u64 v[110:111], v[2:3], 0, v[110:111]
	v_lshl_add_u64 v[106:107], v[2:3], 0, v[106:107]
	v_lshl_add_u64 v[108:109], v[2:3], 0, v[108:109]
	global_load_dword v102, v[110:111], off nt
	global_load_dword v153, v[108:109], off nt
	global_load_dword v154, v[106:107], off nt
	global_load_dword v155, v[104:105], off nt
	s_add_i32 s25, s25, 16
	s_add_i32 s23, s23, 16
	s_add_i32 s26, s26, -16
	s_cmp_lg_u32 s26, 0
	s_lshl_b32 s30, s25, 1
	s_lshl_b32 s27, s23, 1
	v_or_b32_e32 v45, s30, v10
	s_add_i32 s33, s30, 4
	s_add_i32 s31, s27, 4
	s_add_i32 s34, s27, 8
	s_add_i32 s35, s30, 8
	v_add_u32_e32 v0, s0, v45
	v_or_b32_e32 v63, s33, v10
	v_or_b32_e32 v39, s27, v11
	s_add_i32 s36, s27, 12
	s_add_i32 s37, s30, 12
	s_add_i32 s38, s27, 16
	s_add_i32 s40, s27, 20
	s_add_i32 s42, s27, 24
	s_add_i32 s27, s27, 28
	v_or_b32_e32 v62, s31, v11
	v_or_b32_e32 v64, s34, v11
	v_or_b32_e32 v65, s35, v10
	v_lshlrev_b64 v[56:57], 13, v[0:1]
	v_add_u32_e32 v0, s0, v63
	v_mov_b32_e32 v5, v1
	v_mov_b32_e32 v7, v1
	v_mov_b32_e32 v9, v1
	s_add_i32 s39, s30, 16
	v_add_u32_e32 v4, s22, v39
	v_or_b32_e32 v66, s36, v11
	v_or_b32_e32 v67, s37, v10
	v_or_b32_e32 v68, s38, v11
	v_or_b32_e32 v70, s40, v11
	v_or_b32_e32 v72, s42, v11
	v_or_b32_e32 v74, s27, v11
	v_add_u32_e32 v6, s22, v62
	v_add_u32_e32 v8, s22, v64
	v_lshlrev_b64 v[58:59], 13, v[0:1]
	v_add_u32_e32 v0, s0, v65
	v_mov_b32_e32 v47, v1
	v_mov_b32_e32 v49, v1
	v_mov_b32_e32 v51, v1
	v_mov_b32_e32 v53, v1
	v_mov_b32_e32 v55, v1
	s_add_i32 s41, s30, 20
	v_or_b32_e32 v69, s39, v10
	v_lshlrev_b64 v[4:5], 13, v[4:5]
	v_add_u32_e32 v46, s22, v66
	v_add_u32_e32 v48, s22, v68
	v_add_u32_e32 v50, s22, v70
	v_add_u32_e32 v52, s22, v72
	v_add_u32_e32 v54, s22, v74
	v_lshl_add_u64 v[56:57], v[2:3], 0, v[56:57]
	v_lshlrev_b64 v[6:7], 13, v[6:7]
	v_lshlrev_b64 v[8:9], 13, v[8:9]
	v_lshlrev_b64 v[60:61], 13, v[0:1]
	v_add_u32_e32 v0, s0, v67
	s_add_i32 s43, s30, 24
	v_or_b32_e32 v71, s41, v10
	v_lshl_add_u64 v[4:5], v[2:3], 0, v[4:5]
	v_lshlrev_b64 v[46:47], 13, v[46:47]
	v_lshlrev_b64 v[48:49], 13, v[48:49]
	v_lshlrev_b64 v[50:51], 13, v[50:51]
	v_lshlrev_b64 v[52:53], 13, v[52:53]
	v_lshlrev_b64 v[54:55], 13, v[54:55]
	v_lshl_add_u64 v[58:59], v[2:3], 0, v[58:59]
; #define GAS __attribute__((address_space(1)))
; #define LAS __attribute__((address_space(3)))
; #define LDS_WAIT() asm volatile("s_waitcnt lgkmcnt(0)" ::: "memory")
; __device__ __forceinline__ unsigned pk2(float lo, float hi) { unsigned r; asm("v_cvt_pk_bf16_f32 %0, %1, %2" : "=v"(r) : "v"(lo), "v"(hi)); return r; }
; __device__ __forceinline__ void cvt_item(gfp W, int N, bf16* WT, int Kd, int k0, int n0, int drow0, LAS float* scr, int lane, gfp gk) {
;     ...
;     for (int i = 0; i < 32; ++i) { const int kk = 2 * i + (lane >> 5); scr[kk * 33 + (lane & 31)] = W[(size_t)(k0 + kk) * N + n0 + (lane & 31)]; }
;     const int c = lane & 7;
;     f32x4 ga = (f32x4){1.f, 1.f, 1.f, 1.f}, gb = ga;
;     if (gk != nullptr) { ga = *(const GAS f32x4*)(gk + k0 + 8 * c); gb = *(const GAS f32x4*)(gk + k0 + 8 * c + 4); }
;     LDS_WAIT(); asm volatile("" ::: "memory");
; #pragma unroll
;     for (int j = 0; j < 4; ++j) { const int n = (lane >> 3) + 8 * j; const LAS float* s = scr + (8 * c) * 33 + n;
;         v4u o; o.x = pk2(s[0 * 33] * ga[0], s[1 * 33] * ga[1]); o.y = pk2(s[2 * 33] * ga[2], s[3 * 33] * ga[3]); o.z = pk2(s[4 * 33] * gb[0], s[5 * 33] * gb[1]); o.w = pk2(s[6 * 33] * gb[2], s[7 * 33] * gb[3]);
;         *(GAS v4u*)(WT + (size_t)(drow0 + n) * Kd + k0 + 8 * c) = o; }
;     LDS_WAIT(); asm volatile("" ::: "memory");
	v_lshl_add_u64 v[6:7], v[2:3], 0, v[6:7]
	v_lshl_add_u64 v[8:9], v[2:3], 0, v[8:9]
	global_load_dword v76, v[56:57], off nt
	global_load_dword v77, v[4:5], off nt
	v_lshlrev_b64 v[56:57], 13, v[0:1]
	v_add_u32_e32 v0, s0, v69
	s_add_i32 s30, s30, 28
	v_or_b32_e32 v73, s43, v10
	v_lshl_add_u64 v[46:47], v[2:3], 0, v[46:47]
	v_lshl_add_u64 v[48:49], v[2:3], 0, v[48:49]
	v_lshl_add_u64 v[50:51], v[2:3], 0, v[50:51]
	v_lshl_add_u64 v[52:53], v[2:3], 0, v[52:53]
	v_lshl_add_u64 v[54:55], v[2:3], 0, v[54:55]
	global_load_dword v78, v[58:59], off nt
	global_load_dword v79, v[6:7], off nt
	global_load_dword v80, v[8:9], off nt
	global_load_dword v81, v[46:47], off nt
	global_load_dword v82, v[48:49], off nt
	global_load_dword v83, v[50:51], off nt
	global_load_dword v84, v[52:53], off nt
	global_load_dword v85, v[54:55], off nt
	v_lshl_add_u64 v[6:7], v[2:3], 0, v[56:57]
	v_lshlrev_b64 v[8:9], 13, v[0:1]
	v_add_u32_e32 v0, s0, v71
	v_or_b32_e32 v75, s30, v10
	v_lshl_add_u64 v[4:5], v[2:3], 0, v[60:61]
	global_load_dword v86, v[6:7], off nt
	global_load_dword v87, v[4:5], off nt
	v_lshlrev_b64 v[6:7], 13, v[0:1]
	v_add_u32_e32 v0, s0, v73
	v_lshl_add_u64 v[4:5], v[2:3], 0, v[8:9]
	v_lshlrev_b64 v[8:9], 13, v[0:1]
	v_add_u32_e32 v0, s0, v75
	v_lshlrev_b64 v[46:47], 13, v[0:1]
	v_lshl_add_u64 v[46:47], v[2:3], 0, v[46:47]
	v_lshl_add_u64 v[6:7], v[2:3], 0, v[6:7]
	v_lshl_add_u64 v[8:9], v[2:3], 0, v[8:9]
	global_load_dword v0, v[46:47], off nt
	global_load_dword v88, v[8:9], off nt
	global_load_dword v89, v[6:7], off nt
	global_load_dword v90, v[4:5], off nt
	v_mad_u64_u32 v[104:105], s[30:31], v136, s81, v[12:13]
	v_mad_u64_u32 v[106:107], s[30:31], v101, s81, v[12:13]
	v_mad_u64_u32 v[108:109], s[30:31], v127, s81, v[12:13]
	v_mad_u64_u32 v[110:111], s[30:31], v126, s81, v[12:13]
	v_mad_u64_u32 v[112:113], s[30:31], v129, s81, v[12:13]
	v_mad_u64_u32 v[114:115], s[30:31], v128, s81, v[12:13]
	v_mad_u64_u32 v[116:117], s[30:31], v131, s81, v[12:13]
	v_mad_u64_u32 v[118:119], s[30:31], v130, s81, v[12:13]
	v_mad_u64_u32 v[120:121], s[30:31], v133, s81, v[12:13]
	v_mad_u64_u32 v[122:123], s[30:31], v132, s81, v[12:13]
	v_mad_u64_u32 v[124:125], s[30:31], v135, s81, v[12:13]
	v_mad_u64_u32 v[126:127], s[30:31], v134, s81, v[12:13]
	v_mad_u64_u32 v[128:129], s[30:31], v138, s81, v[12:13]
	v_mad_u64_u32 v[130:131], s[30:31], v137, s81, v[12:13]
	v_mad_u64_u32 v[132:133], s[30:31], v140, s81, v[12:13]
	v_mad_u64_u32 v[134:135], s[30:31], v139, s81, v[12:13]
	s_waitcnt vmcnt(31)
	ds_write_b32 v104, v141
	s_waitcnt vmcnt(30)
	ds_write_b32 v106, v142
	s_waitcnt vmcnt(29)
	ds_write_b32 v108, v143
	s_waitcnt vmcnt(28)
	ds_write_b32 v110, v144
	s_waitcnt vmcnt(20)
	ds_write_b32 v112, v152
	ds_write_b32 v114, v145
	ds_write_b32 v116, v151
	ds_write_b32 v118, v146
	s_waitcnt vmcnt(16)
	ds_write_b32 v120, v155
	ds_write_b32 v122, v147
	ds_write_b32 v124, v154
	ds_write_b32 v126, v148
	ds_write_b32 v128, v153
	ds_write_b32 v130, v149
	ds_write_b32 v132, v102
	ds_write_b32 v134, v150
	v_mad_u64_u32 v[4:5], s[30:31], v45, s81, v[12:13]
	v_mad_u64_u32 v[6:7], s[30:31], v39, s81, v[12:13]
	v_mad_u64_u32 v[8:9], s[30:31], v63, s81, v[12:13]
	v_mad_u64_u32 v[46:47], s[30:31], v62, s81, v[12:13]
	v_mad_u64_u32 v[48:49], s[30:31], v65, s81, v[12:13]
	v_mad_u64_u32 v[50:51], s[30:31], v64, s81, v[12:13]
	v_mad_u64_u32 v[52:53], s[30:31], v67, s81, v[12:13]
	v_mad_u64_u32 v[54:55], s[30:31], v66, s81, v[12:13]
	v_mad_u64_u32 v[56:57], s[30:31], v69, s81, v[12:13]
	v_mad_u64_u32 v[58:59], s[30:31], v68, s81, v[12:13]
	v_mad_u64_u32 v[60:61], s[30:31], v71, s81, v[12:13]
	v_mad_u64_u32 v[62:63], s[30:31], v70, s81, v[12:13]
	v_mad_u64_u32 v[64:65], s[30:31], v73, s81, v[12:13]
	v_mad_u64_u32 v[66:67], s[30:31], v72, s81, v[12:13]
	v_mad_u64_u32 v[68:69], s[30:31], v75, s81, v[12:13]
	v_mad_u64_u32 v[70:71], s[30:31], v74, s81, v[12:13]
	s_waitcnt vmcnt(15)
	ds_write_b32 v4, v76
	s_waitcnt vmcnt(14)
	ds_write_b32 v6, v77
	s_waitcnt vmcnt(13)
	ds_write_b32 v8, v78
	s_waitcnt vmcnt(12)
	ds_write_b32 v46, v79
	s_waitcnt vmcnt(4)
	ds_write_b32 v48, v87
	ds_write_b32 v50, v80
	ds_write_b32 v52, v86
	ds_write_b32 v54, v81
	s_waitcnt vmcnt(0)
	ds_write_b32 v56, v90
	ds_write_b32 v58, v82
	ds_write_b32 v60, v89
	ds_write_b32 v62, v83
	ds_write_b32 v64, v88
	ds_write_b32 v66, v84
	ds_write_b32 v68, v0
	ds_write_b32 v70, v85
	s_add_i32 s25, s25, 16
	s_add_i32 s23, s23, 16
	s_add_i32 s26, s26, -16
	s_cmp_lg_u32 s26, 0
	s_waitcnt lgkmcnt(0)
	ds_read2_b32 v[6:7], v41 offset0:33 offset1:41
	ds_read2_b32 v[8:9], v41 offset1:8
	ds_read2_b32 v[46:47], v41 offset0:66 offset1:74
	ds_read2_b32 v[48:49], v41 offset0:99 offset1:107
	ds_read2_b32 v[50:51], v41 offset0:132 offset1:140
	ds_read2_b32 v[52:53], v41 offset0:165 offset1:173
	ds_read2_b32 v[54:55], v41 offset0:198 offset1:206
	ds_read2_b32 v[56:57], v41 offset0:231 offset1:239
	s_lshl_b32 s0, s0, 1
	v_or_b32_e32 v0, s24, v40
	v_lshl_add_u64 v[58:59], v[18:19], 0, s[0:1]
	v_lshlrev_b32_e32 v0, 11, v0
	v_lshl_add_u64 v[60:61], v[58:59], 0, v[0:1]
	s_waitcnt lgkmcnt(6)
	v_cvt_pk_bf16_f32 v2, v8, v6
	s_waitcnt lgkmcnt(4)
	v_cvt_pk_bf16_f32 v3, v46, v48
	s_waitcnt lgkmcnt(2)
	v_cvt_pk_bf16_f32 v4, v50, v52
	s_waitcnt lgkmcnt(0)
	v_cvt_pk_bf16_f32 v5, v54, v56
	global_store_dwordx4 v[60:61], v[2:5], off nt
	v_or_b32_e32 v0, s24, v42
	v_lshlrev_b32_e32 v0, 11, v0
	v_cvt_pk_bf16_f32 v2, v9, v7
	v_cvt_pk_bf16_f32 v3, v47, v49
	v_cvt_pk_bf16_f32 v4, v51, v53
	v_cvt_pk_bf16_f32 v5, v55, v57
	ds_read2_b32 v[8:9], v41 offset0:16 offset1:24
	ds_read2_b32 v[46:47], v41 offset0:49 offset1:57
	ds_read2_b32 v[48:49], v41 offset0:82 offset1:90
	ds_read2_b32 v[50:51], v41 offset0:115 offset1:123
	ds_read2_b32 v[52:53], v41 offset0:148 offset1:156
	ds_read2_b32 v[54:55], v41 offset0:181 offset1:189
	ds_read2_b32 v[56:57], v41 offset0:214 offset1:222
	ds_read2_b32 v[60:61], v41 offset0:247 offset1:255
	v_lshl_add_u64 v[6:7], v[58:59], 0, v[0:1]
	v_or_b32_e32 v0, s24, v43
	v_lshlrev_b32_e32 v0, 11, v0
	global_store_dwordx4 v[6:7], v[2:5], off nt
	v_lshl_add_u64 v[6:7], v[58:59], 0, v[0:1]
	v_or_b32_e32 v0, s24, v44
	v_lshlrev_b32_e32 v0, 11, v0
	s_waitcnt lgkmcnt(6)
	v_cvt_pk_bf16_f32 v2, v8, v46
	s_waitcnt lgkmcnt(4)
	v_cvt_pk_bf16_f32 v3, v48, v50
	s_waitcnt lgkmcnt(2)
	v_cvt_pk_bf16_f32 v4, v52, v54
	s_waitcnt lgkmcnt(0)
	v_cvt_pk_bf16_f32 v5, v56, v60
	global_store_dwordx4 v[6:7], v[2:5], off nt
	v_lshl_add_u64 v[6:7], v[58:59], 0, v[0:1]
	s_nop 0
	v_cvt_pk_bf16_f32 v2, v9, v47
	v_cvt_pk_bf16_f32 v3, v49, v51
	v_cvt_pk_bf16_f32 v4, v53, v55
	v_cvt_pk_bf16_f32 v5, v57, v61
	global_store_dwordx4 v[6:7], v[2:5], off nt
	s_waitcnt lgkmcnt(0)

; __device__ __forceinline__ void cvt_item(gfp W, int N, bf16* WT, int Kd, int k0, int n0, int drow0, LAS float* scr, int lane, gfp gk) {
; #pragma unroll 8
;     for (int i = 0; i < 32; ++i) { const int kk = 2 * i + (lane >> 5); scr[kk * 33 + (lane & 31)] = W[(size_t)(k0 + kk) * N + n0 + (lane & 31)]; }
.LBB0_132:
	v_mov_b32_e32 v103, v1
	s_lshl_b32 s30, s25, 1
	s_lshl_b32 s27, s24, 1
	v_or_b32_e32 v136, s30, v10
	s_add_i32 s33, s30, 4
	s_add_i32 s31, s27, 4
	s_add_i32 s34, s27, 8
	s_add_i32 s35, s30, 8
	v_add_u32_e32 v102, s0, v136
	v_or_b32_e32 v127, s33, v10
	v_or_b32_e32 v101, s27, v11
	s_add_i32 s36, s27, 12
	s_add_i32 s37, s30, 12
	s_add_i32 s38, s27, 16
	s_add_i32 s40, s27, 20
	s_add_i32 s42, s27, 24
	s_add_i32 s27, s27, 28
	v_or_b32_e32 v126, s31, v11
	v_or_b32_e32 v128, s34, v11
	v_or_b32_e32 v129, s35, v10
	v_lshlrev_b64 v[120:121], 13, v[102:103]
	v_add_u32_e32 v102, s0, v127
	v_mov_b32_e32 v105, v103
	v_mov_b32_e32 v107, v103
	v_mov_b32_e32 v109, v103
	s_add_i32 s39, s30, 16
	v_add_u32_e32 v104, s23, v101
	v_or_b32_e32 v130, s36, v11
	v_or_b32_e32 v131, s37, v10
	v_or_b32_e32 v132, s38, v11
	v_or_b32_e32 v134, s40, v11
	v_or_b32_e32 v137, s42, v11
	v_or_b32_e32 v139, s27, v11
	v_add_u32_e32 v106, s23, v126
	v_add_u32_e32 v108, s23, v128
	v_lshlrev_b64 v[122:123], 13, v[102:103]
	v_add_u32_e32 v102, s0, v129
	v_mov_b32_e32 v111, v103
	v_mov_b32_e32 v113, v103
	v_mov_b32_e32 v115, v103
	v_mov_b32_e32 v117, v103
	v_mov_b32_e32 v119, v103
	s_add_i32 s41, s30, 20
	v_or_b32_e32 v133, s39, v10
	v_lshlrev_b64 v[104:105], 13, v[104:105]
	v_add_u32_e32 v110, s23, v130
	v_add_u32_e32 v112, s23, v132
	v_add_u32_e32 v114, s23, v134
	v_add_u32_e32 v116, s23, v137
	v_add_u32_e32 v118, s23, v139
	v_lshl_add_u64 v[120:121], v[2:3], 0, v[120:121]
	v_lshlrev_b64 v[106:107], 13, v[106:107]
	v_lshlrev_b64 v[108:109], 13, v[108:109]
	v_lshlrev_b64 v[124:125], 13, v[102:103]
	v_add_u32_e32 v102, s0, v131
	s_add_i32 s43, s30, 24
	v_or_b32_e32 v135, s41, v10
	v_lshl_add_u64 v[104:105], v[2:3], 0, v[104:105]
	v_lshlrev_b64 v[110:111], 13, v[110:111]
	v_lshlrev_b64 v[112:113], 13, v[112:113]
	v_lshlrev_b64 v[114:115], 13, v[114:115]
	v_lshlrev_b64 v[116:117], 13, v[116:117]
	v_lshlrev_b64 v[118:119], 13, v[118:119]
	v_lshl_add_u64 v[122:123], v[2:3], 0, v[122:123]
	v_lshl_add_u64 v[106:107], v[2:3], 0, v[106:107]
	v_lshl_add_u64 v[108:109], v[2:3], 0, v[108:109]
	global_load_dword v141, v[120:121], off nt
	global_load_dword v142, v[104:105], off nt
	v_lshlrev_b64 v[120:121], 13, v[102:103]
	v_add_u32_e32 v102, s0, v133
	s_add_i32 s30, s30, 28
	v_or_b32_e32 v138, s43, v10
	v_lshl_add_u64 v[110:111], v[2:3], 0, v[110:111]
	v_lshl_add_u64 v[112:113], v[2:3], 0, v[112:113]
	v_lshl_add_u64 v[114:115], v[2:3], 0, v[114:115]
	v_lshl_add_u64 v[116:117], v[2:3], 0, v[116:117]
	v_lshl_add_u64 v[118:119], v[2:3], 0, v[118:119]
	global_load_dword v143, v[122:123], off nt
	global_load_dword v144, v[106:107], off nt
	global_load_dword v145, v[108:109], off nt
	global_load_dword v146, v[110:111], off nt
	global_load_dword v147, v[112:113], off nt
	global_load_dword v148, v[114:115], off nt
	global_load_dword v149, v[116:117], off nt
	global_load_dword v150, v[118:119], off nt
	v_lshl_add_u64 v[106:107], v[2:3], 0, v[120:121]
	v_lshlrev_b64 v[108:109], 13, v[102:103]
	v_add_u32_e32 v102, s0, v135
	v_or_b32_e32 v140, s30, v10
	v_lshl_add_u64 v[104:105], v[2:3], 0, v[124:125]
	global_load_dword v151, v[106:107], off nt
	global_load_dword v152, v[104:105], off nt
	v_lshlrev_b64 v[106:107], 13, v[102:103]
	v_add_u32_e32 v102, s0, v138
	v_lshl_add_u64 v[104:105], v[2:3], 0, v[108:109]
	v_lshlrev_b64 v[108:109], 13, v[102:103]
	v_add_u32_e32 v102, s0, v140
	v_lshlrev_b64 v[110:111], 13, v[102:103]
	v_lshl_add_u64 v[110:111], v[2:3], 0, v[110:111]
	v_lshl_add_u64 v[106:107], v[2:3], 0, v[106:107]
	v_lshl_add_u64 v[108:109], v[2:3], 0, v[108:109]
	global_load_dword v102, v[110:111], off nt
	global_load_dword v153, v[108:109], off nt
	global_load_dword v154, v[106:107], off nt
	global_load_dword v155, v[104:105], off nt
	s_add_i32 s25, s25, 16
	s_add_i32 s24, s24, 16
	s_add_i32 s26, s26, -16
	s_cmp_lg_u32 s26, 0
	s_lshl_b32 s30, s25, 1
	s_lshl_b32 s27, s24, 1
	v_or_b32_e32 v45, s30, v10
	s_add_i32 s33, s30, 4
	s_add_i32 s31, s27, 4
	s_add_i32 s34, s27, 8
	s_add_i32 s35, s30, 8
	v_add_u32_e32 v0, s0, v45
	v_or_b32_e32 v63, s33, v10
	v_or_b32_e32 v39, s27, v11
	s_add_i32 s36, s27, 12
	s_add_i32 s37, s30, 12
	s_add_i32 s38, s27, 16
	s_add_i32 s40, s27, 20
	s_add_i32 s42, s27, 24
	s_add_i32 s27, s27, 28
	v_or_b32_e32 v62, s31, v11
	v_or_b32_e32 v64, s34, v11
	v_or_b32_e32 v65, s35, v10
	v_lshlrev_b64 v[56:57], 13, v[0:1]
	v_add_u32_e32 v0, s0, v63
	v_mov_b32_e32 v5, v1
	v_mov_b32_e32 v7, v1
	v_mov_b32_e32 v9, v1
	s_add_i32 s39, s30, 16
	v_add_u32_e32 v4, s23, v39
	v_or_b32_e32 v66, s36, v11
	v_or_b32_e32 v67, s37, v10
	v_or_b32_e32 v68, s38, v11
	v_or_b32_e32 v70, s40, v11
	v_or_b32_e32 v72, s42, v11
	v_or_b32_e32 v74, s27, v11
	v_add_u32_e32 v6, s23, v62
	v_add_u32_e32 v8, s23, v64
	v_lshlrev_b64 v[58:59], 13, v[0:1]
	v_add_u32_e32 v0, s0, v65
	v_mov_b32_e32 v47, v1
	v_mov_b32_e32 v49, v1
	v_mov_b32_e32 v51, v1
	v_mov_b32_e32 v53, v1
	v_mov_b32_e32 v55, v1
	s_add_i32 s41, s30, 20
	v_or_b32_e32 v69, s39, v10
	v_lshlrev_b64 v[4:5], 13, v[4:5]
	v_add_u32_e32 v46, s23, v66
	v_add_u32_e32 v48, s23, v68
	v_add_u32_e32 v50, s23, v70
	v_add_u32_e32 v52, s23, v72
	v_add_u32_e32 v54, s23, v74
	v_lshl_add_u64 v[56:57], v[2:3], 0, v[56:57]
	v_lshlrev_b64 v[6:7], 13, v[6:7]
	v_lshlrev_b64 v[8:9], 13, v[8:9]
	v_lshlrev_b64 v[60:61], 13, v[0:1]
	v_add_u32_e32 v0, s0, v67
	s_add_i32 s43, s30, 24
	v_or_b32_e32 v71, s41, v10
	v_lshl_add_u64 v[4:5], v[2:3], 0, v[4:5]
	v_lshlrev_b64 v[46:47], 13, v[46:47]
	v_lshlrev_b64 v[48:49], 13, v[48:49]
	v_lshlrev_b64 v[50:51], 13, v[50:51]
	v_lshlrev_b64 v[52:53], 13, v[52:53]
	v_lshlrev_b64 v[54:55], 13, v[54:55]
	v_lshl_add_u64 v[58:59], v[2:3], 0, v[58:59]
; #define GAS __attribute__((address_space(1)))
; #define LAS __attribute__((address_space(3)))
; #define LDS_WAIT() asm volatile("s_waitcnt lgkmcnt(0)" ::: "memory")
; __device__ __forceinline__ unsigned pk2(float lo, float hi) { unsigned r; asm("v_cvt_pk_bf16_f32 %0, %1, %2" : "=v"(r) : "v"(lo), "v"(hi)); return r; }
; __device__ __forceinline__ void cvt_item(gfp W, int N, bf16* WT, int Kd, int k0, int n0, int drow0, LAS float* scr, int lane, gfp gk) {
;     ...
;     for (int i = 0; i < 32; ++i) { const int kk = 2 * i + (lane >> 5); scr[kk * 33 + (lane & 31)] = W[(size_t)(k0 + kk) * N + n0 + (lane & 31)]; }
;     const int c = lane & 7;
;     f32x4 ga = (f32x4){1.f, 1.f, 1.f, 1.f}, gb = ga;
;     if (gk != nullptr) { ga = *(const GAS f32x4*)(gk + k0 + 8 * c); gb = *(const GAS f32x4*)(gk + k0 + 8 * c + 4); }
;     LDS_WAIT(); asm volatile("" ::: "memory");
; #pragma unroll
;     for (int j = 0; j < 4; ++j) { const int n = (lane >> 3) + 8 * j; const LAS float* s = scr + (8 * c) * 33 + n;
;         v4u o; o.x = pk2(s[0 * 33] * ga[0], s[1 * 33] * ga[1]); o.y = pk2(s[2 * 33] * ga[2], s[3 * 33] * ga[3]); o.z = pk2(s[4 * 33] * gb[0], s[5 * 33] * gb[1]); o.w = pk2(s[6 * 33] * gb[2], s[7 * 33] * gb[3]);
;         *(GAS v4u*)(WT + (size_t)(drow0 + n) * Kd + k0 + 8 * c) = o; }
;     LDS_WAIT(); asm volatile("" ::: "memory");
	v_lshl_add_u64 v[6:7], v[2:3], 0, v[6:7]
	v_lshl_add_u64 v[8:9], v[2:3], 0, v[8:9]
	global_load_dword v76, v[56:57], off nt
	global_load_dword v77, v[4:5], off nt
	v_lshlrev_b64 v[56:57], 13, v[0:1]
	v_add_u32_e32 v0, s0, v69
	s_add_i32 s30, s30, 28
	v_or_b32_e32 v73, s43, v10
	v_lshl_add_u64 v[46:47], v[2:3], 0, v[46:47]
	v_lshl_add_u64 v[48:49], v[2:3], 0, v[48:49]
	v_lshl_add_u64 v[50:51], v[2:3], 0, v[50:51]
	v_lshl_add_u64 v[52:53], v[2:3], 0, v[52:53]
	v_lshl_add_u64 v[54:55], v[2:3], 0, v[54:55]
	global_load_dword v78, v[58:59], off nt
	global_load_dword v79, v[6:7], off nt
	global_load_dword v80, v[8:9], off nt
	global_load_dword v81, v[46:47], off nt
	global_load_dword v82, v[48:49], off nt
	global_load_dword v83, v[50:51], off nt
	global_load_dword v84, v[52:53], off nt
	global_load_dword v85, v[54:55], off nt
	v_lshl_add_u64 v[6:7], v[2:3], 0, v[56:57]
	v_lshlrev_b64 v[8:9], 13, v[0:1]
	v_add_u32_e32 v0, s0, v71
	v_or_b32_e32 v75, s30, v10
	v_lshl_add_u64 v[4:5], v[2:3], 0, v[60:61]
	global_load_dword v86, v[6:7], off nt
	global_load_dword v87, v[4:5], off nt
	v_lshlrev_b64 v[6:7], 13, v[0:1]
	v_add_u32_e32 v0, s0, v73
	v_lshl_add_u64 v[4:5], v[2:3], 0, v[8:9]
	v_lshlrev_b64 v[8:9], 13, v[0:1]
	v_add_u32_e32 v0, s0, v75
	v_lshlrev_b64 v[46:47], 13, v[0:1]
	v_lshl_add_u64 v[46:47], v[2:3], 0, v[46:47]
	v_lshl_add_u64 v[6:7], v[2:3], 0, v[6:7]
	v_lshl_add_u64 v[8:9], v[2:3], 0, v[8:9]
	global_load_dword v0, v[46:47], off nt
	global_load_dword v88, v[8:9], off nt
	global_load_dword v89, v[6:7], off nt
	global_load_dword v90, v[4:5], off nt
	v_mad_u64_u32 v[104:105], s[30:31], v136, s81, v[12:13]
	v_mad_u64_u32 v[106:107], s[30:31], v101, s81, v[12:13]
	v_mad_u64_u32 v[108:109], s[30:31], v127, s81, v[12:13]
	v_mad_u64_u32 v[110:111], s[30:31], v126, s81, v[12:13]
	v_mad_u64_u32 v[112:113], s[30:31], v129, s81, v[12:13]
	v_mad_u64_u32 v[114:115], s[30:31], v128, s81, v[12:13]
	v_mad_u64_u32 v[116:117], s[30:31], v131, s81, v[12:13]
	v_mad_u64_u32 v[118:119], s[30:31], v130, s81, v[12:13]
	v_mad_u64_u32 v[120:121], s[30:31], v133, s81, v[12:13]
	v_mad_u64_u32 v[122:123], s[30:31], v132, s81, v[12:13]
	v_mad_u64_u32 v[124:125], s[30:31], v135, s81, v[12:13]
	v_mad_u64_u32 v[126:127], s[30:31], v134, s81, v[12:13]
	v_mad_u64_u32 v[128:129], s[30:31], v138, s81, v[12:13]
	v_mad_u64_u32 v[130:131], s[30:31], v137, s81, v[12:13]
	v_mad_u64_u32 v[132:133], s[30:31], v140, s81, v[12:13]
	v_mad_u64_u32 v[134:135], s[30:31], v139, s81, v[12:13]
	s_waitcnt vmcnt(31)
	ds_write_b32 v104, v141
	s_waitcnt vmcnt(30)
	ds_write_b32 v106, v142
	s_waitcnt vmcnt(29)
	ds_write_b32 v108, v143
	s_waitcnt vmcnt(28)
	ds_write_b32 v110, v144
	s_waitcnt vmcnt(20)
	ds_write_b32 v112, v152
	ds_write_b32 v114, v145
	ds_write_b32 v116, v151
	ds_write_b32 v118, v146
	s_waitcnt vmcnt(16)
	ds_write_b32 v120, v155
	ds_write_b32 v122, v147
	ds_write_b32 v124, v154
	ds_write_b32 v126, v148
	ds_write_b32 v128, v153
	ds_write_b32 v130, v149
	ds_write_b32 v132, v102
	ds_write_b32 v134, v150
	v_mad_u64_u32 v[4:5], s[30:31], v45, s81, v[12:13]
	v_mad_u64_u32 v[6:7], s[30:31], v39, s81, v[12:13]
	v_mad_u64_u32 v[8:9], s[30:31], v63, s81, v[12:13]
	v_mad_u64_u32 v[46:47], s[30:31], v62, s81, v[12:13]
	v_mad_u64_u32 v[48:49], s[30:31], v65, s81, v[12:13]
	v_mad_u64_u32 v[50:51], s[30:31], v64, s81, v[12:13]
	v_mad_u64_u32 v[52:53], s[30:31], v67, s81, v[12:13]
	v_mad_u64_u32 v[54:55], s[30:31], v66, s81, v[12:13]
	v_mad_u64_u32 v[56:57], s[30:31], v69, s81, v[12:13]
	v_mad_u64_u32 v[58:59], s[30:31], v68, s81, v[12:13]
	v_mad_u64_u32 v[60:61], s[30:31], v71, s81, v[12:13]
	v_mad_u64_u32 v[62:63], s[30:31], v70, s81, v[12:13]
	v_mad_u64_u32 v[64:65], s[30:31], v73, s81, v[12:13]
	v_mad_u64_u32 v[66:67], s[30:31], v72, s81, v[12:13]
	v_mad_u64_u32 v[68:69], s[30:31], v75, s81, v[12:13]
	v_mad_u64_u32 v[70:71], s[30:31], v74, s81, v[12:13]
	s_waitcnt vmcnt(15)
	ds_write_b32 v4, v76
	s_waitcnt vmcnt(14)
	ds_write_b32 v6, v77
	s_waitcnt vmcnt(13)
	ds_write_b32 v8, v78
	s_waitcnt vmcnt(12)
	ds_write_b32 v46, v79
	s_waitcnt vmcnt(4)
	ds_write_b32 v48, v87
	ds_write_b32 v50, v80
	ds_write_b32 v52, v86
	ds_write_b32 v54, v81
	s_waitcnt vmcnt(0)
	ds_write_b32 v56, v90
	ds_write_b32 v58, v82
	ds_write_b32 v60, v89
	ds_write_b32 v62, v83
	ds_write_b32 v64, v88
	ds_write_b32 v66, v84
	ds_write_b32 v68, v0
	ds_write_b32 v70, v85
	s_add_i32 s25, s25, 16
	s_add_i32 s24, s24, 16
	s_add_i32 s26, s26, -16
	s_cmp_lg_u32 s26, 0
	s_waitcnt lgkmcnt(0)
	ds_read2_b32 v[6:7], v41 offset0:33 offset1:41
	ds_read2_b32 v[8:9], v41 offset1:8
	ds_read2_b32 v[46:47], v41 offset0:66 offset1:74
	ds_read2_b32 v[48:49], v41 offset0:99 offset1:107
	ds_read2_b32 v[50:51], v41 offset0:132 offset1:140
	ds_read2_b32 v[52:53], v41 offset0:165 offset1:173
	ds_read2_b32 v[54:55], v41 offset0:198 offset1:206
	ds_read2_b32 v[56:57], v41 offset0:231 offset1:239
	s_and_b32 s22, 0xffff, s22
	s_lshl_b32 s0, s0, 1
	v_or_b32_e32 v0, s22, v40
	v_lshl_add_u64 v[58:59], v[20:21], 0, s[0:1]
	v_lshlrev_b32_e32 v0, 11, v0
	v_lshl_add_u64 v[60:61], v[58:59], 0, v[0:1]
	s_waitcnt lgkmcnt(6)
	v_cvt_pk_bf16_f32 v2, v8, v6
	s_waitcnt lgkmcnt(4)
	v_cvt_pk_bf16_f32 v3, v46, v48
	s_waitcnt lgkmcnt(2)
	v_cvt_pk_bf16_f32 v4, v50, v52
	s_waitcnt lgkmcnt(0)
	v_cvt_pk_bf16_f32 v5, v54, v56
	global_store_dwordx4 v[60:61], v[2:5], off nt
	v_or_b32_e32 v0, s22, v42
	v_lshlrev_b32_e32 v0, 11, v0
	v_cvt_pk_bf16_f32 v2, v9, v7
	v_cvt_pk_bf16_f32 v3, v47, v49
	v_cvt_pk_bf16_f32 v4, v51, v53
	v_cvt_pk_bf16_f32 v5, v55, v57
	ds_read2_b32 v[8:9], v41 offset0:16 offset1:24
	ds_read2_b32 v[46:47], v41 offset0:49 offset1:57
	ds_read2_b32 v[48:49], v41 offset0:82 offset1:90
	ds_read2_b32 v[50:51], v41 offset0:115 offset1:123
	ds_read2_b32 v[52:53], v41 offset0:148 offset1:156
	ds_read2_b32 v[54:55], v41 offset0:181 offset1:189
	ds_read2_b32 v[56:57], v41 offset0:214 offset1:222
	ds_read2_b32 v[60:61], v41 offset0:247 offset1:255
	v_lshl_add_u64 v[6:7], v[58:59], 0, v[0:1]
	v_or_b32_e32 v0, s22, v43
	v_lshlrev_b32_e32 v0, 11, v0
	global_store_dwordx4 v[6:7], v[2:5], off nt
	v_lshl_add_u64 v[6:7], v[58:59], 0, v[0:1]
	v_or_b32_e32 v0, s22, v44
	v_lshlrev_b32_e32 v0, 11, v0
	s_waitcnt lgkmcnt(6)
	v_cvt_pk_bf16_f32 v2, v8, v46
	s_waitcnt lgkmcnt(4)
	v_cvt_pk_bf16_f32 v3, v48, v50
	s_waitcnt lgkmcnt(2)
	v_cvt_pk_bf16_f32 v4, v52, v54
	s_waitcnt lgkmcnt(0)
	v_cvt_pk_bf16_f32 v5, v56, v60
	global_store_dwordx4 v[6:7], v[2:5], off nt
	v_lshl_add_u64 v[6:7], v[58:59], 0, v[0:1]
	s_nop 0
	v_cvt_pk_bf16_f32 v2, v9, v47
	v_cvt_pk_bf16_f32 v3, v49, v51
	v_cvt_pk_bf16_f32 v4, v53, v55
	v_cvt_pk_bf16_f32 v5, v57, v61
	global_store_dwordx4 v[6:7], v[2:5], off nt
	s_waitcnt lgkmcnt(0)

; __device__ __forceinline__ void cvt_item(gfp W, int N, bf16* WT, int Kd, int k0, int n0, int drow0, LAS float* scr, int lane, gfp gk) {
; #pragma unroll 8
;     for (int i = 0; i < 32; ++i) { const int kk = 2 * i + (lane >> 5); scr[kk * 33 + (lane & 31)] = W[(size_t)(k0 + kk) * N + n0 + (lane & 31)]; }
.LBB0_137:
	v_mov_b32_e32 v103, v1
	s_lshl_b32 s30, s25, 1
	s_lshl_b32 s27, s24, 1
	v_or_b32_e32 v136, s30, v10
	s_add_i32 s33, s30, 4
	s_add_i32 s31, s27, 4
	s_add_i32 s34, s27, 8
	s_add_i32 s35, s30, 8
	v_add_u32_e32 v102, s0, v136
	v_or_b32_e32 v127, s33, v10
	v_or_b32_e32 v101, s27, v11
	s_add_i32 s36, s27, 12
	s_add_i32 s37, s30, 12
	s_add_i32 s38, s27, 16
	s_add_i32 s40, s27, 20
	s_add_i32 s42, s27, 24
	s_add_i32 s27, s27, 28
	v_or_b32_e32 v126, s31, v11
	v_or_b32_e32 v128, s34, v11
	v_or_b32_e32 v129, s35, v10
	v_lshlrev_b64 v[120:121], 13, v[102:103]
	v_add_u32_e32 v102, s0, v127
	v_mov_b32_e32 v105, v103
	v_mov_b32_e32 v107, v103
	v_mov_b32_e32 v109, v103
	s_add_i32 s39, s30, 16
	v_add_u32_e32 v104, s23, v101
	v_or_b32_e32 v130, s36, v11
	v_or_b32_e32 v131, s37, v10
	v_or_b32_e32 v132, s38, v11
	v_or_b32_e32 v134, s40, v11
	v_or_b32_e32 v137, s42, v11
	v_or_b32_e32 v139, s27, v11
	v_add_u32_e32 v106, s23, v126
	v_add_u32_e32 v108, s23, v128
	v_lshlrev_b64 v[122:123], 13, v[102:103]
	v_add_u32_e32 v102, s0, v129
	v_mov_b32_e32 v111, v103
	v_mov_b32_e32 v113, v103
	v_mov_b32_e32 v115, v103
	v_mov_b32_e32 v117, v103
	v_mov_b32_e32 v119, v103
	s_add_i32 s41, s30, 20
	v_or_b32_e32 v133, s39, v10
	v_lshlrev_b64 v[104:105], 13, v[104:105]
	v_add_u32_e32 v110, s23, v130
	v_add_u32_e32 v112, s23, v132
	v_add_u32_e32 v114, s23, v134
	v_add_u32_e32 v116, s23, v137
	v_add_u32_e32 v118, s23, v139
	v_lshl_add_u64 v[120:121], v[2:3], 0, v[120:121]
	v_lshlrev_b64 v[106:107], 13, v[106:107]
	v_lshlrev_b64 v[108:109], 13, v[108:109]
	v_lshlrev_b64 v[124:125], 13, v[102:103]
	v_add_u32_e32 v102, s0, v131
	s_add_i32 s43, s30, 24
	v_or_b32_e32 v135, s41, v10
	v_lshl_add_u64 v[104:105], v[2:3], 0, v[104:105]
	v_lshlrev_b64 v[110:111], 13, v[110:111]
	v_lshlrev_b64 v[112:113], 13, v[112:113]
	v_lshlrev_b64 v[114:115], 13, v[114:115]
	v_lshlrev_b64 v[116:117], 13, v[116:117]
	v_lshlrev_b64 v[118:119], 13, v[118:119]
	v_lshl_add_u64 v[122:123], v[2:3], 0, v[122:123]
	v_lshl_add_u64 v[106:107], v[2:3], 0, v[106:107]
	v_lshl_add_u64 v[108:109], v[2:3], 0, v[108:109]
	global_load_dword v141, v[120:121], off nt
	global_load_dword v142, v[104:105], off nt
	v_lshlrev_b64 v[120:121], 13, v[102:103]
	v_add_u32_e32 v102, s0, v133
	s_add_i32 s30, s30, 28
	v_or_b32_e32 v138, s43, v10
	v_lshl_add_u64 v[110:111], v[2:3], 0, v[110:111]
	v_lshl_add_u64 v[112:113], v[2:3], 0, v[112:113]
	v_lshl_add_u64 v[114:115], v[2:3], 0, v[114:115]
	v_lshl_add_u64 v[116:117], v[2:3], 0, v[116:117]
	v_lshl_add_u64 v[118:119], v[2:3], 0, v[118:119]
	global_load_dword v143, v[122:123], off nt
	global_load_dword v144, v[106:107], off nt
	global_load_dword v145, v[108:109], off nt
	global_load_dword v146, v[110:111], off nt
	global_load_dword v147, v[112:113], off nt
	global_load_dword v148, v[114:115], off nt
	global_load_dword v149, v[116:117], off nt
	global_load_dword v150, v[118:119], off nt
	v_lshl_add_u64 v[106:107], v[2:3], 0, v[120:121]
	v_lshlrev_b64 v[108:109], 13, v[102:103]
	v_add_u32_e32 v102, s0, v135
	v_or_b32_e32 v140, s30, v10
	v_lshl_add_u64 v[104:105], v[2:3], 0, v[124:125]
	global_load_dword v151, v[106:107], off nt
	global_load_dword v152, v[104:105], off nt
	v_lshlrev_b64 v[106:107], 13, v[102:103]
	v_add_u32_e32 v102, s0, v138
	v_lshl_add_u64 v[104:105], v[2:3], 0, v[108:109]
	v_lshlrev_b64 v[108:109], 13, v[102:103]
	v_add_u32_e32 v102, s0, v140
	v_lshlrev_b64 v[110:111], 13, v[102:103]
	v_lshl_add_u64 v[110:111], v[2:3], 0, v[110:111]
	v_lshl_add_u64 v[106:107], v[2:3], 0, v[106:107]
	v_lshl_add_u64 v[108:109], v[2:3], 0, v[108:109]
	global_load_dword v102, v[110:111], off nt
	global_load_dword v153, v[108:109], off nt
	global_load_dword v154, v[106:107], off nt
	global_load_dword v155, v[104:105], off nt
	s_add_i32 s25, s25, 16
	s_add_i32 s24, s24, 16
	s_add_i32 s26, s26, -16
	s_cmp_lg_u32 s26, 0
	s_lshl_b32 s30, s25, 1
	s_lshl_b32 s27, s24, 1
	v_or_b32_e32 v45, s30, v10
	s_add_i32 s33, s30, 4
	s_add_i32 s31, s27, 4
	s_add_i32 s34, s27, 8
	s_add_i32 s35, s30, 8
	v_add_u32_e32 v0, s0, v45
	v_or_b32_e32 v63, s33, v10
	v_or_b32_e32 v39, s27, v11
	s_add_i32 s36, s27, 12
	s_add_i32 s37, s30, 12
	s_add_i32 s38, s27, 16
	s_add_i32 s40, s27, 20
	s_add_i32 s42, s27, 24
	s_add_i32 s27, s27, 28
	v_or_b32_e32 v62, s31, v11
	v_or_b32_e32 v64, s34, v11
	v_or_b32_e32 v65, s35, v10
	v_lshlrev_b64 v[56:57], 13, v[0:1]
	v_add_u32_e32 v0, s0, v63
	v_mov_b32_e32 v5, v1
	v_mov_b32_e32 v7, v1
	v_mov_b32_e32 v9, v1
	s_add_i32 s39, s30, 16
	v_add_u32_e32 v4, s23, v39
	v_or_b32_e32 v66, s36, v11
	v_or_b32_e32 v67, s37, v10
	v_or_b32_e32 v68, s38, v11
	v_or_b32_e32 v70, s40, v11
	v_or_b32_e32 v72, s42, v11
	v_or_b32_e32 v74, s27, v11
	v_add_u32_e32 v6, s23, v62
	v_add_u32_e32 v8, s23, v64
	v_lshlrev_b64 v[58:59], 13, v[0:1]
	v_add_u32_e32 v0, s0, v65
	v_mov_b32_e32 v47, v1
	v_mov_b32_e32 v49, v1
	v_mov_b32_e32 v51, v1
	v_mov_b32_e32 v53, v1
	v_mov_b32_e32 v55, v1
	s_add_i32 s41, s30, 20
	v_or_b32_e32 v69, s39, v10
	v_lshlrev_b64 v[4:5], 13, v[4:5]
	v_add_u32_e32 v46, s23, v66
	v_add_u32_e32 v48, s23, v68
	v_add_u32_e32 v50, s23, v70
	v_add_u32_e32 v52, s23, v72
	v_add_u32_e32 v54, s23, v74
	v_lshl_add_u64 v[56:57], v[2:3], 0, v[56:57]
	v_lshlrev_b64 v[6:7], 13, v[6:7]
	v_lshlrev_b64 v[8:9], 13, v[8:9]
	v_lshlrev_b64 v[60:61], 13, v[0:1]
	v_add_u32_e32 v0, s0, v67
	s_add_i32 s43, s30, 24
	v_or_b32_e32 v71, s41, v10
	v_lshl_add_u64 v[4:5], v[2:3], 0, v[4:5]
	v_lshlrev_b64 v[46:47], 13, v[46:47]
	v_lshlrev_b64 v[48:49], 13, v[48:49]
	v_lshlrev_b64 v[50:51], 13, v[50:51]
	v_lshlrev_b64 v[52:53], 13, v[52:53]
	v_lshlrev_b64 v[54:55], 13, v[54:55]
	v_lshl_add_u64 v[58:59], v[2:3], 0, v[58:59]
; #define GAS __attribute__((address_space(1)))
; #define LAS __attribute__((address_space(3)))
; #define LDS_WAIT() asm volatile("s_waitcnt lgkmcnt(0)" ::: "memory")
; __device__ __forceinline__ unsigned pk2(float lo, float hi) { unsigned r; asm("v_cvt_pk_bf16_f32 %0, %1, %2" : "=v"(r) : "v"(lo), "v"(hi)); return r; }
; __device__ __forceinline__ void cvt_item(gfp W, int N, bf16* WT, int Kd, int k0, int n0, int drow0, LAS float* scr, int lane, gfp gk) {
;     ...
;     for (int i = 0; i < 32; ++i) { const int kk = 2 * i + (lane >> 5); scr[kk * 33 + (lane & 31)] = W[(size_t)(k0 + kk) * N + n0 + (lane & 31)]; }
;     const int c = lane & 7;
;     f32x4 ga = (f32x4){1.f, 1.f, 1.f, 1.f}, gb = ga;
;     if (gk != nullptr) { ga = *(const GAS f32x4*)(gk + k0 + 8 * c); gb = *(const GAS f32x4*)(gk + k0 + 8 * c + 4); }
;     LDS_WAIT(); asm volatile("" ::: "memory");
; #pragma unroll
;     for (int j = 0; j < 4; ++j) { const int n = (lane >> 3) + 8 * j; const LAS float* s = scr + (8 * c) * 33 + n;
;         v4u o; o.x = pk2(s[0 * 33] * ga[0], s[1 * 33] * ga[1]); o.y = pk2(s[2 * 33] * ga[2], s[3 * 33] * ga[3]); o.z = pk2(s[4 * 33] * gb[0], s[5 * 33] * gb[1]); o.w = pk2(s[6 * 33] * gb[2], s[7 * 33] * gb[3]);
;         *(GAS v4u*)(WT + (size_t)(drow0 + n) * Kd + k0 + 8 * c) = o; }
;     LDS_WAIT(); asm volatile("" ::: "memory");
	v_lshl_add_u64 v[6:7], v[2:3], 0, v[6:7]
	v_lshl_add_u64 v[8:9], v[2:3], 0, v[8:9]
	global_load_dword v76, v[56:57], off nt
	global_load_dword v77, v[4:5], off nt
	v_lshlrev_b64 v[56:57], 13, v[0:1]
	v_add_u32_e32 v0, s0, v69
	s_add_i32 s30, s30, 28
	v_or_b32_e32 v73, s43, v10
	v_lshl_add_u64 v[46:47], v[2:3], 0, v[46:47]
	v_lshl_add_u64 v[48:49], v[2:3], 0, v[48:49]
	v_lshl_add_u64 v[50:51], v[2:3], 0, v[50:51]
	v_lshl_add_u64 v[52:53], v[2:3], 0, v[52:53]
	v_lshl_add_u64 v[54:55], v[2:3], 0, v[54:55]
	global_load_dword v78, v[58:59], off nt
	global_load_dword v79, v[6:7], off nt
	global_load_dword v80, v[8:9], off nt
	global_load_dword v81, v[46:47], off nt
	global_load_dword v82, v[48:49], off nt
	global_load_dword v83, v[50:51], off nt
	global_load_dword v84, v[52:53], off nt
	global_load_dword v85, v[54:55], off nt
	v_lshl_add_u64 v[6:7], v[2:3], 0, v[56:57]
	v_lshlrev_b64 v[8:9], 13, v[0:1]
	v_add_u32_e32 v0, s0, v71
	v_or_b32_e32 v75, s30, v10
	v_lshl_add_u64 v[4:5], v[2:3], 0, v[60:61]
	global_load_dword v86, v[6:7], off nt
	global_load_dword v87, v[4:5], off nt
	v_lshlrev_b64 v[6:7], 13, v[0:1]
	v_add_u32_e32 v0, s0, v73
	v_lshl_add_u64 v[4:5], v[2:3], 0, v[8:9]
	v_lshlrev_b64 v[8:9], 13, v[0:1]
	v_add_u32_e32 v0, s0, v75
	v_lshlrev_b64 v[46:47], 13, v[0:1]
	v_lshl_add_u64 v[46:47], v[2:3], 0, v[46:47]
	v_lshl_add_u64 v[6:7], v[2:3], 0, v[6:7]
	v_lshl_add_u64 v[8:9], v[2:3], 0, v[8:9]
	global_load_dword v0, v[46:47], off nt
	global_load_dword v88, v[8:9], off nt
	global_load_dword v89, v[6:7], off nt
	global_load_dword v90, v[4:5], off nt
	v_mad_u64_u32 v[104:105], s[30:31], v136, s81, v[12:13]
	v_mad_u64_u32 v[106:107], s[30:31], v101, s81, v[12:13]
	v_mad_u64_u32 v[108:109], s[30:31], v127, s81, v[12:13]
	v_mad_u64_u32 v[110:111], s[30:31], v126, s81, v[12:13]
	v_mad_u64_u32 v[112:113], s[30:31], v129, s81, v[12:13]
	v_mad_u64_u32 v[114:115], s[30:31], v128, s81, v[12:13]
	v_mad_u64_u32 v[116:117], s[30:31], v131, s81, v[12:13]
	v_mad_u64_u32 v[118:119], s[30:31], v130, s81, v[12:13]
	v_mad_u64_u32 v[120:121], s[30:31], v133, s81, v[12:13]
	v_mad_u64_u32 v[122:123], s[30:31], v132, s81, v[12:13]
	v_mad_u64_u32 v[124:125], s[30:31], v135, s81, v[12:13]
	v_mad_u64_u32 v[126:127], s[30:31], v134, s81, v[12:13]
	v_mad_u64_u32 v[128:129], s[30:31], v138, s81, v[12:13]
	v_mad_u64_u32 v[130:131], s[30:31], v137, s81, v[12:13]
	v_mad_u64_u32 v[132:133], s[30:31], v140, s81, v[12:13]
	v_mad_u64_u32 v[134:135], s[30:31], v139, s81, v[12:13]
	s_waitcnt vmcnt(31)
	ds_write_b32 v104, v141
	s_waitcnt vmcnt(30)
	ds_write_b32 v106, v142
	s_waitcnt vmcnt(29)
	ds_write_b32 v108, v143
	s_waitcnt vmcnt(28)
	ds_write_b32 v110, v144
	s_waitcnt vmcnt(20)
	ds_write_b32 v112, v152
	ds_write_b32 v114, v145
	ds_write_b32 v116, v151
	ds_write_b32 v118, v146
	s_waitcnt vmcnt(16)
	ds_write_b32 v120, v155
	ds_write_b32 v122, v147
	ds_write_b32 v124, v154
	ds_write_b32 v126, v148
	ds_write_b32 v128, v153
	ds_write_b32 v130, v149
	ds_write_b32 v132, v102
	ds_write_b32 v134, v150
	v_mad_u64_u32 v[4:5], s[30:31], v45, s81, v[12:13]
	v_mad_u64_u32 v[6:7], s[30:31], v39, s81, v[12:13]
	v_mad_u64_u32 v[8:9], s[30:31], v63, s81, v[12:13]
	v_mad_u64_u32 v[46:47], s[30:31], v62, s81, v[12:13]
	v_mad_u64_u32 v[48:49], s[30:31], v65, s81, v[12:13]
	v_mad_u64_u32 v[50:51], s[30:31], v64, s81, v[12:13]
	v_mad_u64_u32 v[52:53], s[30:31], v67, s81, v[12:13]
	v_mad_u64_u32 v[54:55], s[30:31], v66, s81, v[12:13]
	v_mad_u64_u32 v[56:57], s[30:31], v69, s81, v[12:13]
	v_mad_u64_u32 v[58:59], s[30:31], v68, s81, v[12:13]
	v_mad_u64_u32 v[60:61], s[30:31], v71, s81, v[12:13]
	v_mad_u64_u32 v[62:63], s[30:31], v70, s81, v[12:13]
	v_mad_u64_u32 v[64:65], s[30:31], v73, s81, v[12:13]
	v_mad_u64_u32 v[66:67], s[30:31], v72, s81, v[12:13]
	v_mad_u64_u32 v[68:69], s[30:31], v75, s81, v[12:13]
	v_mad_u64_u32 v[70:71], s[30:31], v74, s81, v[12:13]
	s_waitcnt vmcnt(15)
	ds_write_b32 v4, v76
	s_waitcnt vmcnt(14)
	ds_write_b32 v6, v77
	s_waitcnt vmcnt(13)
	ds_write_b32 v8, v78
	s_waitcnt vmcnt(12)
	ds_write_b32 v46, v79
	s_waitcnt vmcnt(4)
	ds_write_b32 v48, v87
	ds_write_b32 v50, v80
	ds_write_b32 v52, v86
	ds_write_b32 v54, v81
	s_waitcnt vmcnt(0)
	ds_write_b32 v56, v90
	ds_write_b32 v58, v82
	ds_write_b32 v60, v89
	ds_write_b32 v62, v83
	ds_write_b32 v64, v88
	ds_write_b32 v66, v84
	ds_write_b32 v68, v0
	ds_write_b32 v70, v85
	s_add_i32 s25, s25, 16
	s_add_i32 s24, s24, 16
	s_add_i32 s26, s26, -16
	s_cmp_lg_u32 s26, 0
	s_waitcnt lgkmcnt(0)
	ds_read2_b32 v[6:7], v41 offset0:33 offset1:41
	ds_read2_b32 v[8:9], v41 offset1:8
	ds_read2_b32 v[46:47], v41 offset0:66 offset1:74
	ds_read2_b32 v[48:49], v41 offset0:99 offset1:107
	ds_read2_b32 v[50:51], v41 offset0:132 offset1:140
	ds_read2_b32 v[52:53], v41 offset0:165 offset1:173
	ds_read2_b32 v[54:55], v41 offset0:198 offset1:206
	ds_read2_b32 v[56:57], v41 offset0:231 offset1:239
	s_and_b32 s22, 0xffff, s22
	s_lshl_b32 s0, s0, 1
	v_or_b32_e32 v0, s22, v40
	v_lshl_add_u64 v[58:59], v[22:23], 0, s[0:1]
	v_lshlrev_b32_e32 v0, 11, v0
	v_lshl_add_u64 v[60:61], v[58:59], 0, v[0:1]
	s_waitcnt lgkmcnt(6)
	v_cvt_pk_bf16_f32 v2, v8, v6
	s_waitcnt lgkmcnt(4)
	v_cvt_pk_bf16_f32 v3, v46, v48
	s_waitcnt lgkmcnt(2)
	v_cvt_pk_bf16_f32 v4, v50, v52
	s_waitcnt lgkmcnt(0)
	v_cvt_pk_bf16_f32 v5, v54, v56
	global_store_dwordx4 v[60:61], v[2:5], off nt
	v_or_b32_e32 v0, s22, v42
	v_lshlrev_b32_e32 v0, 11, v0
	v_cvt_pk_bf16_f32 v2, v9, v7
	v_cvt_pk_bf16_f32 v3, v47, v49
	v_cvt_pk_bf16_f32 v4, v51, v53
	v_cvt_pk_bf16_f32 v5, v55, v57
	ds_read2_b32 v[8:9], v41 offset0:16 offset1:24
	ds_read2_b32 v[46:47], v41 offset0:49 offset1:57
	ds_read2_b32 v[48:49], v41 offset0:82 offset1:90
	ds_read2_b32 v[50:51], v41 offset0:115 offset1:123
	ds_read2_b32 v[52:53], v41 offset0:148 offset1:156
	ds_read2_b32 v[54:55], v41 offset0:181 offset1:189
	ds_read2_b32 v[56:57], v41 offset0:214 offset1:222
	ds_read2_b32 v[60:61], v41 offset0:247 offset1:255
	v_lshl_add_u64 v[6:7], v[58:59], 0, v[0:1]
	v_or_b32_e32 v0, s22, v43
	v_lshlrev_b32_e32 v0, 11, v0
	global_store_dwordx4 v[6:7], v[2:5], off nt
	v_lshl_add_u64 v[6:7], v[58:59], 0, v[0:1]
	v_or_b32_e32 v0, s22, v44
	v_lshlrev_b32_e32 v0, 11, v0
	s_waitcnt lgkmcnt(6)
	v_cvt_pk_bf16_f32 v2, v8, v46
	s_waitcnt lgkmcnt(4)
	v_cvt_pk_bf16_f32 v3, v48, v50
	s_waitcnt lgkmcnt(2)
	v_cvt_pk_bf16_f32 v4, v52, v54
	s_waitcnt lgkmcnt(0)
	v_cvt_pk_bf16_f32 v5, v56, v60
	global_store_dwordx4 v[6:7], v[2:5], off nt
	v_lshl_add_u64 v[6:7], v[58:59], 0, v[0:1]
	s_nop 0
	v_cvt_pk_bf16_f32 v2, v9, v47
	v_cvt_pk_bf16_f32 v3, v49, v51
	v_cvt_pk_bf16_f32 v4, v53, v55
	v_cvt_pk_bf16_f32 v5, v57, v61
	global_store_dwordx4 v[6:7], v[2:5], off nt
	s_waitcnt lgkmcnt(0)

; #define GAS __attribute__((address_space(1)))
; #define LAS __attribute__((address_space(3)))
; #define LDS_WAIT() asm volatile("s_waitcnt lgkmcnt(0)" ::: "memory")
; __device__ __forceinline__ unsigned pk2(float lo, float hi) { unsigned r; asm("v_cvt_pk_bf16_f32 %0, %1, %2" : "=v"(r) : "v"(lo), "v"(hi)); return r; }
; __device__ __forceinline__ void cvt_item(gfp W, int N, bf16* WT, int Kd, int k0, int n0, int drow0, LAS float* scr, int lane, gfp gk) {
;     ...
;     LDS_WAIT(); asm volatile("" ::: "memory");
; #pragma unroll
;     for (int j = 0; j < 4; ++j) { const int n = (lane >> 3) + 8 * j; const LAS float* s = scr + (8 * c) * 33 + n;
;         v4u o; o.x = pk2(s[0 * 33] * ga[0], s[1 * 33] * ga[1]); o.y = pk2(s[2 * 33] * ga[2], s[3 * 33] * ga[3]); o.z = pk2(s[4 * 33] * gb[0], s[5 * 33] * gb[1]); o.w = pk2(s[6 * 33] * gb[2], s[7 * 33] * gb[3]);
;         *(GAS v4u*)(WT + (size_t)(drow0 + n) * Kd + k0 + 8 * c) = o; }
;     LDS_WAIT(); asm volatile("" ::: "memory");
.LBB0_147:
	s_waitcnt lgkmcnt(0)
	ds_read2_b32 v[50:51], v41 offset1:8
	ds_read2_b32 v[52:53], v41 offset0:33 offset1:41
	ds_read2_b32 v[56:57], v41 offset0:66 offset1:74
	ds_read2_b32 v[58:59], v41 offset0:99 offset1:107
	ds_read2_b32 v[60:61], v41 offset0:132 offset1:140
	ds_read2_b32 v[62:63], v41 offset0:165 offset1:173
	ds_read2_b32 v[64:65], v41 offset0:198 offset1:206
	ds_read2_b32 v[66:67], v41 offset0:231 offset1:239
	s_waitcnt vmcnt(0) lgkmcnt(7)
	v_mul_f32_e32 v0, v6, v50
	s_waitcnt lgkmcnt(6)
	v_mul_f32_e32 v39, v7, v52
	v_cvt_pk_bf16_f32 v46, v0, v39
	s_waitcnt lgkmcnt(5)
	v_mul_f32_e32 v0, v8, v56
	s_waitcnt lgkmcnt(4)
	v_mul_f32_e32 v39, v9, v58
	v_cvt_pk_bf16_f32 v47, v0, v39
	s_waitcnt lgkmcnt(3)
	v_mul_f32_e32 v0, v2, v60
	s_and_b32 s22, 0xffff, s24
	s_waitcnt lgkmcnt(2)
	v_mul_f32_e32 v39, v3, v62
	v_cvt_pk_bf16_f32 v48, v0, v39
	s_waitcnt lgkmcnt(1)
	v_mul_f32_e32 v0, v4, v64
	s_lshl_b32 s0, s0, 1
	s_waitcnt lgkmcnt(0)
	v_mul_f32_e32 v39, v5, v66
	v_cvt_pk_bf16_f32 v49, v0, v39
	v_or_b32_e32 v0, s22, v40
	v_lshl_add_u64 v[54:55], v[28:29], 0, s[0:1]
	v_lshlrev_b32_e32 v0, 10, v0
	v_lshl_add_u64 v[68:69], v[54:55], 0, v[0:1]
	v_mul_f32_e32 v0, v6, v51
	global_store_dwordx4 v[68:69], v[46:49], off nt
	v_mul_f32_e32 v39, v7, v53
	s_nop 0
	v_cvt_pk_bf16_f32 v46, v0, v39
	v_mul_f32_e32 v0, v8, v57
	v_mul_f32_e32 v39, v9, v59
	v_cvt_pk_bf16_f32 v47, v0, v39
	v_mul_f32_e32 v0, v2, v61
	v_mul_f32_e32 v39, v3, v63
	v_cvt_pk_bf16_f32 v48, v0, v39
	v_mul_f32_e32 v0, v4, v65
	v_mul_f32_e32 v39, v5, v67
	v_cvt_pk_bf16_f32 v49, v0, v39
	v_or_b32_e32 v0, s22, v42
	v_lshlrev_b32_e32 v0, 10, v0
	v_lshl_add_u64 v[50:51], v[54:55], 0, v[0:1]
	ds_read2_b32 v[52:53], v41 offset0:16 offset1:24
	ds_read2_b32 v[56:57], v41 offset0:49 offset1:57
	global_store_dwordx4 v[50:51], v[46:49], off nt
	ds_read2_b32 v[50:51], v41 offset0:82 offset1:90
	ds_read2_b32 v[58:59], v41 offset0:115 offset1:123
	ds_read2_b32 v[60:61], v41 offset0:148 offset1:156
	ds_read2_b32 v[62:63], v41 offset0:181 offset1:189
	ds_read2_b32 v[64:65], v41 offset0:214 offset1:222
	ds_read2_b32 v[66:67], v41 offset0:247 offset1:255
	s_waitcnt lgkmcnt(7)
	v_mul_f32_e32 v0, v6, v52
	s_waitcnt lgkmcnt(6)
	v_mul_f32_e32 v39, v7, v56
	v_cvt_pk_bf16_f32 v46, v0, v39
	s_waitcnt lgkmcnt(5)
	v_mul_f32_e32 v0, v8, v50
	s_waitcnt lgkmcnt(4)
	v_mul_f32_e32 v39, v9, v58
	v_cvt_pk_bf16_f32 v47, v0, v39
	s_waitcnt lgkmcnt(3)
	v_mul_f32_e32 v0, v2, v60
	s_waitcnt lgkmcnt(2)
	v_mul_f32_e32 v39, v3, v62
	v_cvt_pk_bf16_f32 v48, v0, v39
	s_waitcnt lgkmcnt(1)
	v_mul_f32_e32 v0, v4, v64
	s_waitcnt lgkmcnt(0)
	v_mul_f32_e32 v39, v5, v66
	v_cvt_pk_bf16_f32 v49, v0, v39
	v_or_b32_e32 v0, s22, v43
	v_lshlrev_b32_e32 v0, 10, v0
	v_lshl_add_u64 v[68:69], v[54:55], 0, v[0:1]
	v_mul_f32_e32 v0, v6, v53
	v_mul_f32_e32 v6, v7, v57
	v_cvt_pk_bf16_f32 v6, v0, v6
	v_mul_f32_e32 v0, v8, v51
	v_mul_f32_e32 v7, v9, v59
	v_cvt_pk_bf16_f32 v7, v0, v7
	v_mul_f32_e32 v0, v2, v61
	v_mul_f32_e32 v2, v3, v63
	v_cvt_pk_bf16_f32 v8, v0, v2
	v_mul_f32_e32 v0, v4, v65
	v_mul_f32_e32 v2, v5, v67
	v_cvt_pk_bf16_f32 v9, v0, v2
	v_or_b32_e32 v0, s22, v44
	v_lshlrev_b32_e32 v0, 10, v0
	v_lshl_add_u64 v[2:3], v[54:55], 0, v[0:1]
	global_store_dwordx4 v[68:69], v[46:49], off nt
	global_store_dwordx4 v[2:3], v[6:9], off nt
	s_waitcnt lgkmcnt(0)

; #define GAS __attribute__((address_space(1)))
; #define LAS __attribute__((address_space(3)))
; #define LDS_WAIT() asm volatile("s_waitcnt lgkmcnt(0)" ::: "memory")
; __device__ __forceinline__ unsigned pk2(float lo, float hi) { unsigned r; asm("v_cvt_pk_bf16_f32 %0, %1, %2" : "=v"(r) : "v"(lo), "v"(hi)); return r; }
; __device__ __forceinline__ void cvt_item(gfp W, int N, bf16* WT, int Kd, int k0, int n0, int drow0, LAS float* scr, int lane, gfp gk) {
;     ...
;     LDS_WAIT(); asm volatile("" ::: "memory");
; #pragma unroll
;     for (int j = 0; j < 4; ++j) { const int n = (lane >> 3) + 8 * j; const LAS float* s = scr + (8 * c) * 33 + n;
;         v4u o; o.x = pk2(s[0 * 33] * ga[0], s[1 * 33] * ga[1]); o.y = pk2(s[2 * 33] * ga[2], s[3 * 33] * ga[3]); o.z = pk2(s[4 * 33] * gb[0], s[5 * 33] * gb[1]); o.w = pk2(s[6 * 33] * gb[2], s[7 * 33] * gb[3]);
;         *(GAS v4u*)(WT + (size_t)(drow0 + n) * Kd + k0 + 8 * c) = o; }
;     LDS_WAIT(); asm volatile("" ::: "memory");
.LBB0_155:
	s_waitcnt lgkmcnt(0)
	ds_read2_b32 v[50:51], v41 offset1:8
	ds_read2_b32 v[52:53], v41 offset0:33 offset1:41
	ds_read2_b32 v[56:57], v41 offset0:66 offset1:74
	ds_read2_b32 v[58:59], v41 offset0:99 offset1:107
	ds_read2_b32 v[60:61], v41 offset0:132 offset1:140
	ds_read2_b32 v[62:63], v41 offset0:165 offset1:173
	ds_read2_b32 v[64:65], v41 offset0:198 offset1:206
	ds_read2_b32 v[66:67], v41 offset0:231 offset1:239
	s_waitcnt vmcnt(0) lgkmcnt(7)
	v_mul_f32_e32 v0, v6, v50
	s_waitcnt lgkmcnt(6)
	v_mul_f32_e32 v39, v7, v52
	v_cvt_pk_bf16_f32 v46, v0, v39
	s_waitcnt lgkmcnt(5)
	v_mul_f32_e32 v0, v8, v56
	s_waitcnt lgkmcnt(4)
	v_mul_f32_e32 v39, v9, v58
	v_cvt_pk_bf16_f32 v47, v0, v39
	s_waitcnt lgkmcnt(3)
	v_mul_f32_e32 v0, v2, v60
	s_and_b32 s22, 0xffff, s24
	s_waitcnt lgkmcnt(2)
	v_mul_f32_e32 v39, v3, v62
	v_cvt_pk_bf16_f32 v48, v0, v39
	s_waitcnt lgkmcnt(1)
	v_mul_f32_e32 v0, v4, v64
	s_lshl_b32 s0, s0, 1
	s_waitcnt lgkmcnt(0)
	v_mul_f32_e32 v39, v5, v66
	v_cvt_pk_bf16_f32 v49, v0, v39
	v_or_b32_e32 v0, s22, v40
	v_lshl_add_u64 v[54:55], v[30:31], 0, s[0:1]
	v_lshlrev_b32_e32 v0, 10, v0
	v_lshl_add_u64 v[68:69], v[54:55], 0, v[0:1]
	v_mul_f32_e32 v0, v6, v51
	global_store_dwordx4 v[68:69], v[46:49], off nt
	v_mul_f32_e32 v39, v7, v53
	s_nop 0
	v_cvt_pk_bf16_f32 v46, v0, v39
	v_mul_f32_e32 v0, v8, v57
	v_mul_f32_e32 v39, v9, v59
	v_cvt_pk_bf16_f32 v47, v0, v39
	v_mul_f32_e32 v0, v2, v61
	v_mul_f32_e32 v39, v3, v63
	v_cvt_pk_bf16_f32 v48, v0, v39
	v_mul_f32_e32 v0, v4, v65
	v_mul_f32_e32 v39, v5, v67
	v_cvt_pk_bf16_f32 v49, v0, v39
	v_or_b32_e32 v0, s22, v42
	v_lshlrev_b32_e32 v0, 10, v0
	v_lshl_add_u64 v[50:51], v[54:55], 0, v[0:1]
	ds_read2_b32 v[52:53], v41 offset0:16 offset1:24
	ds_read2_b32 v[56:57], v41 offset0:49 offset1:57
	global_store_dwordx4 v[50:51], v[46:49], off nt
	ds_read2_b32 v[50:51], v41 offset0:82 offset1:90
	ds_read2_b32 v[58:59], v41 offset0:115 offset1:123
	ds_read2_b32 v[60:61], v41 offset0:148 offset1:156
	ds_read2_b32 v[62:63], v41 offset0:181 offset1:189
	ds_read2_b32 v[64:65], v41 offset0:214 offset1:222
	ds_read2_b32 v[66:67], v41 offset0:247 offset1:255
	s_waitcnt lgkmcnt(7)
	v_mul_f32_e32 v0, v6, v52
	s_waitcnt lgkmcnt(6)
	v_mul_f32_e32 v39, v7, v56
	v_cvt_pk_bf16_f32 v46, v0, v39
	s_waitcnt lgkmcnt(5)
	v_mul_f32_e32 v0, v8, v50
	s_waitcnt lgkmcnt(4)
	v_mul_f32_e32 v39, v9, v58
	v_cvt_pk_bf16_f32 v47, v0, v39
	s_waitcnt lgkmcnt(3)
	v_mul_f32_e32 v0, v2, v60
	s_waitcnt lgkmcnt(2)
	v_mul_f32_e32 v39, v3, v62
	v_cvt_pk_bf16_f32 v48, v0, v39
	s_waitcnt lgkmcnt(1)
	v_mul_f32_e32 v0, v4, v64
	s_waitcnt lgkmcnt(0)
	v_mul_f32_e32 v39, v5, v66
	v_cvt_pk_bf16_f32 v49, v0, v39
	v_or_b32_e32 v0, s22, v43
	v_lshlrev_b32_e32 v0, 10, v0
	v_lshl_add_u64 v[68:69], v[54:55], 0, v[0:1]
	v_mul_f32_e32 v0, v6, v53
	v_mul_f32_e32 v6, v7, v57
	v_cvt_pk_bf16_f32 v6, v0, v6
	v_mul_f32_e32 v0, v8, v51
	v_mul_f32_e32 v7, v9, v59
	v_cvt_pk_bf16_f32 v7, v0, v7
	v_mul_f32_e32 v0, v2, v61
	v_mul_f32_e32 v2, v3, v63
	v_cvt_pk_bf16_f32 v8, v0, v2
	v_mul_f32_e32 v0, v4, v65
	v_mul_f32_e32 v2, v5, v67
	v_cvt_pk_bf16_f32 v9, v0, v2
	v_or_b32_e32 v0, s22, v44
	v_lshlrev_b32_e32 v0, 10, v0
	v_lshl_add_u64 v[2:3], v[54:55], 0, v[0:1]
	global_store_dwordx4 v[68:69], v[46:49], off nt
	global_store_dwordx4 v[2:3], v[6:9], off nt
	s_waitcnt lgkmcnt(0)

; #define GAS __attribute__((address_space(1)))
; #define LAS __attribute__((address_space(3)))
; #define LDS_WAIT() asm volatile("s_waitcnt lgkmcnt(0)" ::: "memory")
; __device__ __forceinline__ unsigned pk2(float lo, float hi) { unsigned r; asm("v_cvt_pk_bf16_f32 %0, %1, %2" : "=v"(r) : "v"(lo), "v"(hi)); return r; }
; __device__ __forceinline__ void cvt_item(gfp W, int N, bf16* WT, int Kd, int k0, int n0, int drow0, LAS float* scr, int lane, gfp gk) {
;     ...
;     LDS_WAIT(); asm volatile("" ::: "memory");
; #pragma unroll
;     for (int j = 0; j < 4; ++j) { const int n = (lane >> 3) + 8 * j; const LAS float* s = scr + (8 * c) * 33 + n;
;         v4u o; o.x = pk2(s[0 * 33] * ga[0], s[1 * 33] * ga[1]); o.y = pk2(s[2 * 33] * ga[2], s[3 * 33] * ga[3]); o.z = pk2(s[4 * 33] * gb[0], s[5 * 33] * gb[1]); o.w = pk2(s[6 * 33] * gb[2], s[7 * 33] * gb[3]);
;         *(GAS v4u*)(WT + (size_t)(drow0 + n) * Kd + k0 + 8 * c) = o; }
;     LDS_WAIT(); asm volatile("" ::: "memory");
.LBB0_163:
	s_waitcnt lgkmcnt(0)
	ds_read2_b32 v[50:51], v41 offset1:8
	ds_read2_b32 v[52:53], v41 offset0:33 offset1:41
	ds_read2_b32 v[56:57], v41 offset0:66 offset1:74
	ds_read2_b32 v[58:59], v41 offset0:99 offset1:107
	ds_read2_b32 v[60:61], v41 offset0:132 offset1:140
	ds_read2_b32 v[62:63], v41 offset0:165 offset1:173
	ds_read2_b32 v[64:65], v41 offset0:198 offset1:206
	ds_read2_b32 v[66:67], v41 offset0:231 offset1:239
	s_waitcnt vmcnt(0) lgkmcnt(7)
	v_mul_f32_e32 v0, v6, v50
	s_waitcnt lgkmcnt(6)
	v_mul_f32_e32 v39, v7, v52
	v_cvt_pk_bf16_f32 v46, v0, v39
	s_waitcnt lgkmcnt(5)
	v_mul_f32_e32 v0, v8, v56
	s_waitcnt lgkmcnt(4)
	v_mul_f32_e32 v39, v9, v58
	v_cvt_pk_bf16_f32 v47, v0, v39
	s_waitcnt lgkmcnt(3)
	v_mul_f32_e32 v0, v2, v60
	s_and_b32 s22, 0xffff, s0
	s_waitcnt lgkmcnt(2)
	v_mul_f32_e32 v39, v3, v62
	v_cvt_pk_bf16_f32 v48, v0, v39
	s_waitcnt lgkmcnt(1)
	v_mul_f32_e32 v0, v4, v64
	s_lshl_b32 s0, s24, 1
	s_waitcnt lgkmcnt(0)
	v_mul_f32_e32 v39, v5, v66
	v_cvt_pk_bf16_f32 v49, v0, v39
	v_or_b32_e32 v0, s22, v40
	v_lshl_add_u64 v[54:55], v[32:33], 0, s[0:1]
	v_lshlrev_b32_e32 v0, 12, v0
	v_lshl_add_u64 v[68:69], v[54:55], 0, v[0:1]
	v_mul_f32_e32 v0, v6, v51
	global_store_dwordx4 v[68:69], v[46:49], off nt
	v_mul_f32_e32 v39, v7, v53
	s_nop 0
	v_cvt_pk_bf16_f32 v46, v0, v39
	v_mul_f32_e32 v0, v8, v57
	v_mul_f32_e32 v39, v9, v59
	v_cvt_pk_bf16_f32 v47, v0, v39
	v_mul_f32_e32 v0, v2, v61
	v_mul_f32_e32 v39, v3, v63
	v_cvt_pk_bf16_f32 v48, v0, v39
	v_mul_f32_e32 v0, v4, v65
	v_mul_f32_e32 v39, v5, v67
	v_cvt_pk_bf16_f32 v49, v0, v39
	v_or_b32_e32 v0, s22, v42
	v_lshlrev_b32_e32 v0, 12, v0
	v_lshl_add_u64 v[50:51], v[54:55], 0, v[0:1]
	ds_read2_b32 v[52:53], v41 offset0:16 offset1:24
	ds_read2_b32 v[56:57], v41 offset0:49 offset1:57
	global_store_dwordx4 v[50:51], v[46:49], off nt
	ds_read2_b32 v[50:51], v41 offset0:82 offset1:90
	ds_read2_b32 v[58:59], v41 offset0:115 offset1:123
	ds_read2_b32 v[60:61], v41 offset0:148 offset1:156
	ds_read2_b32 v[62:63], v41 offset0:181 offset1:189
	ds_read2_b32 v[64:65], v41 offset0:214 offset1:222
	ds_read2_b32 v[66:67], v41 offset0:247 offset1:255
	s_waitcnt lgkmcnt(7)
	v_mul_f32_e32 v0, v6, v52
	s_waitcnt lgkmcnt(6)
	v_mul_f32_e32 v39, v7, v56
	v_cvt_pk_bf16_f32 v46, v0, v39
	s_waitcnt lgkmcnt(5)
	v_mul_f32_e32 v0, v8, v50
	s_waitcnt lgkmcnt(4)
	v_mul_f32_e32 v39, v9, v58
	v_cvt_pk_bf16_f32 v47, v0, v39
	s_waitcnt lgkmcnt(3)
	v_mul_f32_e32 v0, v2, v60
	s_waitcnt lgkmcnt(2)
	v_mul_f32_e32 v39, v3, v62
	v_cvt_pk_bf16_f32 v48, v0, v39
	s_waitcnt lgkmcnt(1)
	v_mul_f32_e32 v0, v4, v64
	s_waitcnt lgkmcnt(0)
	v_mul_f32_e32 v39, v5, v66
	v_cvt_pk_bf16_f32 v49, v0, v39
	v_or_b32_e32 v0, s22, v43
	v_lshlrev_b32_e32 v0, 12, v0
	v_lshl_add_u64 v[68:69], v[54:55], 0, v[0:1]
	v_mul_f32_e32 v0, v6, v53
	v_mul_f32_e32 v6, v7, v57
	v_cvt_pk_bf16_f32 v6, v0, v6
	v_mul_f32_e32 v0, v8, v51
	v_mul_f32_e32 v7, v9, v59
	v_cvt_pk_bf16_f32 v7, v0, v7
	v_mul_f32_e32 v0, v2, v61
	v_mul_f32_e32 v2, v3, v63
	v_cvt_pk_bf16_f32 v8, v0, v2
	v_mul_f32_e32 v0, v4, v65
	v_mul_f32_e32 v2, v5, v67
	v_cvt_pk_bf16_f32 v9, v0, v2
	v_or_b32_e32 v0, s22, v44
	v_lshlrev_b32_e32 v0, 12, v0
	v_lshl_add_u64 v[2:3], v[54:55], 0, v[0:1]
	global_store_dwordx4 v[68:69], v[46:49], off nt
	global_store_dwordx4 v[2:3], v[6:9], off nt
	s_waitcnt lgkmcnt(0)

; __device__ __forceinline__ void cvt_item(gfp W, int N, bf16* WT, int Kd, int k0, int n0, int drow0, LAS float* scr, int lane, gfp gk) {
; #pragma unroll 8
;     for (int i = 0; i < 32; ++i) { const int kk = 2 * i + (lane >> 5); scr[kk * 33 + (lane & 31)] = W[(size_t)(k0 + kk) * N + n0 + (lane & 31)]; }
.LBB0_167:
	v_mov_b32_e32 v103, v1
	s_lshl_b32 s30, s25, 1
	s_lshl_b32 s27, s24, 1
	v_or_b32_e32 v136, s30, v10
	s_add_i32 s33, s30, 4
	s_add_i32 s31, s27, 4
	s_add_i32 s34, s27, 8
	s_add_i32 s35, s30, 8
	v_add_u32_e32 v102, s0, v136
	v_or_b32_e32 v127, s33, v10
	v_or_b32_e32 v101, s27, v11
	s_add_i32 s36, s27, 12
	s_add_i32 s37, s30, 12
	s_add_i32 s38, s27, 16
	s_add_i32 s40, s27, 20
	s_add_i32 s42, s27, 24
	s_add_i32 s27, s27, 28
	v_or_b32_e32 v126, s31, v11
	v_or_b32_e32 v128, s34, v11
	v_or_b32_e32 v129, s35, v10
	v_lshlrev_b64 v[120:121], 13, v[102:103]
	v_add_u32_e32 v102, s0, v127
	v_mov_b32_e32 v105, v103
	v_mov_b32_e32 v107, v103
	v_mov_b32_e32 v109, v103
	s_add_i32 s39, s30, 16
	v_add_u32_e32 v104, s23, v101
	v_or_b32_e32 v130, s36, v11
	v_or_b32_e32 v131, s37, v10
	v_or_b32_e32 v132, s38, v11
	v_or_b32_e32 v134, s40, v11
	v_or_b32_e32 v137, s42, v11
	v_or_b32_e32 v139, s27, v11
	v_add_u32_e32 v106, s23, v126
	v_add_u32_e32 v108, s23, v128
	v_lshlrev_b64 v[122:123], 13, v[102:103]
	v_add_u32_e32 v102, s0, v129
	v_mov_b32_e32 v111, v103
	v_mov_b32_e32 v113, v103
	v_mov_b32_e32 v115, v103
	v_mov_b32_e32 v117, v103
	v_mov_b32_e32 v119, v103
	s_add_i32 s41, s30, 20
	v_or_b32_e32 v133, s39, v10
	v_lshlrev_b64 v[104:105], 13, v[104:105]
	v_add_u32_e32 v110, s23, v130
	v_add_u32_e32 v112, s23, v132
	v_add_u32_e32 v114, s23, v134
	v_add_u32_e32 v116, s23, v137
	v_add_u32_e32 v118, s23, v139
	v_lshl_add_u64 v[120:121], v[2:3], 0, v[120:121]
	v_lshlrev_b64 v[106:107], 13, v[106:107]
	v_lshlrev_b64 v[108:109], 13, v[108:109]
	v_lshlrev_b64 v[124:125], 13, v[102:103]
	v_add_u32_e32 v102, s0, v131
	s_add_i32 s43, s30, 24
	v_or_b32_e32 v135, s41, v10
	v_lshl_add_u64 v[104:105], v[2:3], 0, v[104:105]
	v_lshlrev_b64 v[110:111], 13, v[110:111]
	v_lshlrev_b64 v[112:113], 13, v[112:113]
	v_lshlrev_b64 v[114:115], 13, v[114:115]
	v_lshlrev_b64 v[116:117], 13, v[116:117]
	v_lshlrev_b64 v[118:119], 13, v[118:119]
	v_lshl_add_u64 v[122:123], v[2:3], 0, v[122:123]
	v_lshl_add_u64 v[106:107], v[2:3], 0, v[106:107]
	v_lshl_add_u64 v[108:109], v[2:3], 0, v[108:109]
	global_load_dword v141, v[120:121], off nt
	global_load_dword v142, v[104:105], off nt
	v_lshlrev_b64 v[120:121], 13, v[102:103]
	v_add_u32_e32 v102, s0, v133
	s_add_i32 s30, s30, 28
	v_or_b32_e32 v138, s43, v10
	v_lshl_add_u64 v[110:111], v[2:3], 0, v[110:111]
	v_lshl_add_u64 v[112:113], v[2:3], 0, v[112:113]
	v_lshl_add_u64 v[114:115], v[2:3], 0, v[114:115]
	v_lshl_add_u64 v[116:117], v[2:3], 0, v[116:117]
	v_lshl_add_u64 v[118:119], v[2:3], 0, v[118:119]
	global_load_dword v143, v[122:123], off nt
	global_load_dword v144, v[106:107], off nt
	global_load_dword v145, v[108:109], off nt
	global_load_dword v146, v[110:111], off nt
	global_load_dword v147, v[112:113], off nt
	global_load_dword v148, v[114:115], off nt
	global_load_dword v149, v[116:117], off nt
	global_load_dword v150, v[118:119], off nt
	v_lshl_add_u64 v[106:107], v[2:3], 0, v[120:121]
	v_lshlrev_b64 v[108:109], 13, v[102:103]
	v_add_u32_e32 v102, s0, v135
	v_or_b32_e32 v140, s30, v10
	v_lshl_add_u64 v[104:105], v[2:3], 0, v[124:125]
	global_load_dword v151, v[106:107], off nt
	global_load_dword v152, v[104:105], off nt
	v_lshlrev_b64 v[106:107], 13, v[102:103]
	v_add_u32_e32 v102, s0, v138
	v_lshl_add_u64 v[104:105], v[2:3], 0, v[108:109]
	v_lshlrev_b64 v[108:109], 13, v[102:103]
	v_add_u32_e32 v102, s0, v140
	v_lshlrev_b64 v[110:111], 13, v[102:103]
	v_lshl_add_u64 v[110:111], v[2:3], 0, v[110:111]
	v_lshl_add_u64 v[106:107], v[2:3], 0, v[106:107]
	v_lshl_add_u64 v[108:109], v[2:3], 0, v[108:109]
	global_load_dword v102, v[110:111], off nt
	global_load_dword v153, v[108:109], off nt
	global_load_dword v154, v[106:107], off nt
	global_load_dword v155, v[104:105], off nt
	s_add_i32 s25, s25, 16
	s_add_i32 s24, s24, 16
	s_add_i32 s26, s26, -16
	s_cmp_lg_u32 s26, 0
	s_lshl_b32 s30, s25, 1
	s_lshl_b32 s27, s24, 1
	v_or_b32_e32 v45, s30, v10
	s_add_i32 s33, s30, 4
	s_add_i32 s31, s27, 4
	s_add_i32 s34, s27, 8
	s_add_i32 s35, s30, 8
	v_add_u32_e32 v0, s0, v45
	v_or_b32_e32 v63, s33, v10
	v_or_b32_e32 v39, s27, v11
	s_add_i32 s36, s27, 12
	s_add_i32 s37, s30, 12
	s_add_i32 s38, s27, 16
	s_add_i32 s40, s27, 20
	s_add_i32 s42, s27, 24
	s_add_i32 s27, s27, 28
	v_or_b32_e32 v62, s31, v11
	v_or_b32_e32 v64, s34, v11
	v_or_b32_e32 v65, s35, v10
	v_lshlrev_b64 v[56:57], 13, v[0:1]
	v_add_u32_e32 v0, s0, v63
	v_mov_b32_e32 v5, v1
	v_mov_b32_e32 v7, v1
	v_mov_b32_e32 v9, v1
	s_add_i32 s39, s30, 16
	v_add_u32_e32 v4, s23, v39
	v_or_b32_e32 v66, s36, v11
	v_or_b32_e32 v67, s37, v10
	v_or_b32_e32 v68, s38, v11
	v_or_b32_e32 v70, s40, v11
	v_or_b32_e32 v72, s42, v11
	v_or_b32_e32 v74, s27, v11
	v_add_u32_e32 v6, s23, v62
	v_add_u32_e32 v8, s23, v64
	v_lshlrev_b64 v[58:59], 13, v[0:1]
	v_add_u32_e32 v0, s0, v65
	v_mov_b32_e32 v47, v1
	v_mov_b32_e32 v49, v1
	v_mov_b32_e32 v51, v1
	v_mov_b32_e32 v53, v1
	v_mov_b32_e32 v55, v1
	s_add_i32 s41, s30, 20
	v_or_b32_e32 v69, s39, v10
	v_lshlrev_b64 v[4:5], 13, v[4:5]
	v_add_u32_e32 v46, s23, v66
	v_add_u32_e32 v48, s23, v68
	v_add_u32_e32 v50, s23, v70
	v_add_u32_e32 v52, s23, v72
	v_add_u32_e32 v54, s23, v74
	v_lshl_add_u64 v[56:57], v[2:3], 0, v[56:57]
	v_lshlrev_b64 v[6:7], 13, v[6:7]
	v_lshlrev_b64 v[8:9], 13, v[8:9]
	v_lshlrev_b64 v[60:61], 13, v[0:1]
	v_add_u32_e32 v0, s0, v67
	s_add_i32 s43, s30, 24
	v_or_b32_e32 v71, s41, v10
	v_lshl_add_u64 v[4:5], v[2:3], 0, v[4:5]
	v_lshlrev_b64 v[46:47], 13, v[46:47]
	v_lshlrev_b64 v[48:49], 13, v[48:49]
	v_lshlrev_b64 v[50:51], 13, v[50:51]
	v_lshlrev_b64 v[52:53], 13, v[52:53]
	v_lshlrev_b64 v[54:55], 13, v[54:55]
	v_lshl_add_u64 v[58:59], v[2:3], 0, v[58:59]
; #define GAS __attribute__((address_space(1)))
; #define LAS __attribute__((address_space(3)))
; #define LDS_WAIT() asm volatile("s_waitcnt lgkmcnt(0)" ::: "memory")
; __device__ __forceinline__ unsigned pk2(float lo, float hi) { unsigned r; asm("v_cvt_pk_bf16_f32 %0, %1, %2" : "=v"(r) : "v"(lo), "v"(hi)); return r; }
; __device__ __forceinline__ void cvt_item(gfp W, int N, bf16* WT, int Kd, int k0, int n0, int drow0, LAS float* scr, int lane, gfp gk) {
;     ...
;     for (int i = 0; i < 32; ++i) { const int kk = 2 * i + (lane >> 5); scr[kk * 33 + (lane & 31)] = W[(size_t)(k0 + kk) * N + n0 + (lane & 31)]; }
;     const int c = lane & 7;
;     f32x4 ga = (f32x4){1.f, 1.f, 1.f, 1.f}, gb = ga;
;     if (gk != nullptr) { ga = *(const GAS f32x4*)(gk + k0 + 8 * c); gb = *(const GAS f32x4*)(gk + k0 + 8 * c + 4); }
;     LDS_WAIT(); asm volatile("" ::: "memory");
; #pragma unroll
;     for (int j = 0; j < 4; ++j) { const int n = (lane >> 3) + 8 * j; const LAS float* s = scr + (8 * c) * 33 + n;
;         v4u o; o.x = pk2(s[0 * 33] * ga[0], s[1 * 33] * ga[1]); o.y = pk2(s[2 * 33] * ga[2], s[3 * 33] * ga[3]); o.z = pk2(s[4 * 33] * gb[0], s[5 * 33] * gb[1]); o.w = pk2(s[6 * 33] * gb[2], s[7 * 33] * gb[3]);
;         *(GAS v4u*)(WT + (size_t)(drow0 + n) * Kd + k0 + 8 * c) = o; }
;     LDS_WAIT(); asm volatile("" ::: "memory");
	v_lshl_add_u64 v[6:7], v[2:3], 0, v[6:7]
	v_lshl_add_u64 v[8:9], v[2:3], 0, v[8:9]
	global_load_dword v76, v[56:57], off nt
	global_load_dword v77, v[4:5], off nt
	v_lshlrev_b64 v[56:57], 13, v[0:1]
	v_add_u32_e32 v0, s0, v69
	s_add_i32 s30, s30, 28
	v_or_b32_e32 v73, s43, v10
	v_lshl_add_u64 v[46:47], v[2:3], 0, v[46:47]
	v_lshl_add_u64 v[48:49], v[2:3], 0, v[48:49]
	v_lshl_add_u64 v[50:51], v[2:3], 0, v[50:51]
	v_lshl_add_u64 v[52:53], v[2:3], 0, v[52:53]
	v_lshl_add_u64 v[54:55], v[2:3], 0, v[54:55]
	global_load_dword v78, v[58:59], off nt
	global_load_dword v79, v[6:7], off nt
	global_load_dword v80, v[8:9], off nt
	global_load_dword v81, v[46:47], off nt
	global_load_dword v82, v[48:49], off nt
	global_load_dword v83, v[50:51], off nt
	global_load_dword v84, v[52:53], off nt
	global_load_dword v85, v[54:55], off nt
	v_lshl_add_u64 v[6:7], v[2:3], 0, v[56:57]
	v_lshlrev_b64 v[8:9], 13, v[0:1]
	v_add_u32_e32 v0, s0, v71
	v_or_b32_e32 v75, s30, v10
	v_lshl_add_u64 v[4:5], v[2:3], 0, v[60:61]
	global_load_dword v86, v[6:7], off nt
	global_load_dword v87, v[4:5], off nt
	v_lshlrev_b64 v[6:7], 13, v[0:1]
	v_add_u32_e32 v0, s0, v73
	v_lshl_add_u64 v[4:5], v[2:3], 0, v[8:9]
	v_lshlrev_b64 v[8:9], 13, v[0:1]
	v_add_u32_e32 v0, s0, v75
	v_lshlrev_b64 v[46:47], 13, v[0:1]
	v_lshl_add_u64 v[46:47], v[2:3], 0, v[46:47]
	v_lshl_add_u64 v[6:7], v[2:3], 0, v[6:7]
	v_lshl_add_u64 v[8:9], v[2:3], 0, v[8:9]
	global_load_dword v0, v[46:47], off nt
	global_load_dword v88, v[8:9], off nt
	global_load_dword v89, v[6:7], off nt
	global_load_dword v90, v[4:5], off nt
	v_mad_u64_u32 v[104:105], s[30:31], v136, s81, v[12:13]
	v_mad_u64_u32 v[106:107], s[30:31], v101, s81, v[12:13]
	v_mad_u64_u32 v[108:109], s[30:31], v127, s81, v[12:13]
	v_mad_u64_u32 v[110:111], s[30:31], v126, s81, v[12:13]
	v_mad_u64_u32 v[112:113], s[30:31], v129, s81, v[12:13]
	v_mad_u64_u32 v[114:115], s[30:31], v128, s81, v[12:13]
	v_mad_u64_u32 v[116:117], s[30:31], v131, s81, v[12:13]
	v_mad_u64_u32 v[118:119], s[30:31], v130, s81, v[12:13]
	v_mad_u64_u32 v[120:121], s[30:31], v133, s81, v[12:13]
	v_mad_u64_u32 v[122:123], s[30:31], v132, s81, v[12:13]
	v_mad_u64_u32 v[124:125], s[30:31], v135, s81, v[12:13]
	v_mad_u64_u32 v[126:127], s[30:31], v134, s81, v[12:13]
	v_mad_u64_u32 v[128:129], s[30:31], v138, s81, v[12:13]
	v_mad_u64_u32 v[130:131], s[30:31], v137, s81, v[12:13]
	v_mad_u64_u32 v[132:133], s[30:31], v140, s81, v[12:13]
	v_mad_u64_u32 v[134:135], s[30:31], v139, s81, v[12:13]
	s_waitcnt vmcnt(31)
	ds_write_b32 v104, v141
	s_waitcnt vmcnt(30)
	ds_write_b32 v106, v142
	s_waitcnt vmcnt(29)
	ds_write_b32 v108, v143
	s_waitcnt vmcnt(28)
	ds_write_b32 v110, v144
	s_waitcnt vmcnt(20)
	ds_write_b32 v112, v152
	ds_write_b32 v114, v145
	ds_write_b32 v116, v151
	ds_write_b32 v118, v146
	s_waitcnt vmcnt(16)
	ds_write_b32 v120, v155
	ds_write_b32 v122, v147
	ds_write_b32 v124, v154
	ds_write_b32 v126, v148
	ds_write_b32 v128, v153
	ds_write_b32 v130, v149
	ds_write_b32 v132, v102
	ds_write_b32 v134, v150
	v_mad_u64_u32 v[4:5], s[30:31], v45, s81, v[12:13]
	v_mad_u64_u32 v[6:7], s[30:31], v39, s81, v[12:13]
	v_mad_u64_u32 v[8:9], s[30:31], v63, s81, v[12:13]
	v_mad_u64_u32 v[46:47], s[30:31], v62, s81, v[12:13]
	v_mad_u64_u32 v[48:49], s[30:31], v65, s81, v[12:13]
	v_mad_u64_u32 v[50:51], s[30:31], v64, s81, v[12:13]
	v_mad_u64_u32 v[52:53], s[30:31], v67, s81, v[12:13]
	v_mad_u64_u32 v[54:55], s[30:31], v66, s81, v[12:13]
	v_mad_u64_u32 v[56:57], s[30:31], v69, s81, v[12:13]
	v_mad_u64_u32 v[58:59], s[30:31], v68, s81, v[12:13]
	v_mad_u64_u32 v[60:61], s[30:31], v71, s81, v[12:13]
	v_mad_u64_u32 v[62:63], s[30:31], v70, s81, v[12:13]
	v_mad_u64_u32 v[64:65], s[30:31], v73, s81, v[12:13]
	v_mad_u64_u32 v[66:67], s[30:31], v72, s81, v[12:13]
	v_mad_u64_u32 v[68:69], s[30:31], v75, s81, v[12:13]
	v_mad_u64_u32 v[70:71], s[30:31], v74, s81, v[12:13]
	s_waitcnt vmcnt(15)
	ds_write_b32 v4, v76
	s_waitcnt vmcnt(14)
	ds_write_b32 v6, v77
	s_waitcnt vmcnt(13)
	ds_write_b32 v8, v78
	s_waitcnt vmcnt(12)
	ds_write_b32 v46, v79
	s_waitcnt vmcnt(4)
	ds_write_b32 v48, v87
	ds_write_b32 v50, v80
	ds_write_b32 v52, v86
	ds_write_b32 v54, v81
	s_waitcnt vmcnt(0)
	ds_write_b32 v56, v90
	ds_write_b32 v58, v82
	ds_write_b32 v60, v89
	ds_write_b32 v62, v83
	ds_write_b32 v64, v88
	ds_write_b32 v66, v84
	ds_write_b32 v68, v0
	ds_write_b32 v70, v85
	s_add_i32 s25, s25, 16
	s_add_i32 s24, s24, 16
	s_add_i32 s26, s26, -16
	s_cmp_lg_u32 s26, 0
	s_and_b32 s22, 0xffff, s22
	s_waitcnt lgkmcnt(0)
	v_or_b32_e32 v0, s22, v40
	s_lshl_b32 s0, s0, 1
	ds_read2_b32 v[6:7], v41 offset0:33 offset1:41
	ds_read2_b32 v[8:9], v41 offset1:8
	ds_read2_b32 v[46:47], v41 offset0:66 offset1:74
	ds_read2_b32 v[48:49], v41 offset0:99 offset1:107
	ds_read2_b32 v[50:51], v41 offset0:132 offset1:140
	ds_read2_b32 v[52:53], v41 offset0:165 offset1:173
	ds_read2_b32 v[54:55], v41 offset0:198 offset1:206
	ds_read2_b32 v[56:57], v41 offset0:231 offset1:239
	v_mul_u32_u24_e32 v0, 0x1600, v0
	v_lshl_add_u64 v[58:59], v[24:25], 0, s[0:1]
	v_lshlrev_b32_e32 v0, 1, v0
	v_lshl_add_u64 v[60:61], v[58:59], 0, v[0:1]
	v_or_b32_e32 v0, s22, v42
	v_mul_u32_u24_e32 v0, 0x1600, v0
	s_waitcnt lgkmcnt(6)
	v_cvt_pk_bf16_f32 v2, v8, v6
	v_lshlrev_b32_e32 v0, 1, v0
	s_waitcnt lgkmcnt(4)
	v_cvt_pk_bf16_f32 v3, v46, v48
	s_waitcnt lgkmcnt(2)
	v_cvt_pk_bf16_f32 v4, v50, v52
	s_waitcnt lgkmcnt(0)
	v_cvt_pk_bf16_f32 v5, v54, v56
	global_store_dwordx4 v[60:61], v[2:5], off nt
	s_nop 1
	v_cvt_pk_bf16_f32 v2, v9, v7
	v_lshl_add_u64 v[6:7], v[58:59], 0, v[0:1]
	v_or_b32_e32 v0, s22, v43
	v_cvt_pk_bf16_f32 v3, v47, v49
	v_cvt_pk_bf16_f32 v4, v51, v53
	v_cvt_pk_bf16_f32 v5, v55, v57
	ds_read2_b32 v[8:9], v41 offset0:16 offset1:24
	ds_read2_b32 v[46:47], v41 offset0:49 offset1:57
	ds_read2_b32 v[48:49], v41 offset0:82 offset1:90
	ds_read2_b32 v[50:51], v41 offset0:115 offset1:123
	ds_read2_b32 v[52:53], v41 offset0:148 offset1:156
	ds_read2_b32 v[54:55], v41 offset0:181 offset1:189
	ds_read2_b32 v[56:57], v41 offset0:214 offset1:222
	ds_read2_b32 v[60:61], v41 offset0:247 offset1:255
	v_mul_u32_u24_e32 v0, 0x1600, v0
	v_lshlrev_b32_e32 v0, 1, v0
	global_store_dwordx4 v[6:7], v[2:5], off nt
	v_lshl_add_u64 v[6:7], v[58:59], 0, v[0:1]
	v_or_b32_e32 v0, s22, v44
	v_mul_u32_u24_e32 v0, 0x1600, v0
	v_lshlrev_b32_e32 v0, 1, v0
	s_waitcnt lgkmcnt(6)
	v_cvt_pk_bf16_f32 v2, v8, v46
	s_waitcnt lgkmcnt(4)
	v_cvt_pk_bf16_f32 v3, v48, v50
	s_waitcnt lgkmcnt(2)
	v_cvt_pk_bf16_f32 v4, v52, v54
	s_waitcnt lgkmcnt(0)
	v_cvt_pk_bf16_f32 v5, v56, v60
	global_store_dwordx4 v[6:7], v[2:5], off nt
	v_lshl_add_u64 v[6:7], v[58:59], 0, v[0:1]
	s_nop 0
	v_cvt_pk_bf16_f32 v2, v9, v47
	v_cvt_pk_bf16_f32 v3, v49, v51
	v_cvt_pk_bf16_f32 v4, v53, v55
	v_cvt_pk_bf16_f32 v5, v57, v61
	global_store_dwordx4 v[6:7], v[2:5], off nt
	s_waitcnt lgkmcnt(0)

; __device__ __forceinline__ void cvt_item(gfp W, int N, bf16* WT, int Kd, int k0, int n0, int drow0, LAS float* scr, int lane, gfp gk) {
; #pragma unroll 8
;     for (int i = 0; i < 32; ++i) { const int kk = 2 * i + (lane >> 5); scr[kk * 33 + (lane & 31)] = W[(size_t)(k0 + kk) * N + n0 + (lane & 31)]; }
.LBB0_172:
	v_mov_b32_e32 v103, v1
	s_lshl_b32 s30, s25, 1
	s_lshl_b32 s27, s24, 1
	v_or_b32_e32 v136, s30, v10
	s_add_i32 s33, s30, 4
	s_add_i32 s31, s27, 4
	s_add_i32 s34, s27, 8
	s_add_i32 s35, s30, 8
	v_add_u32_e32 v102, s0, v136
	v_or_b32_e32 v127, s33, v10
	v_or_b32_e32 v101, s27, v11
	s_add_i32 s36, s27, 12
	s_add_i32 s37, s30, 12
	s_add_i32 s38, s27, 16
	s_add_i32 s40, s27, 20
	s_add_i32 s42, s27, 24
	s_add_i32 s27, s27, 28
	v_or_b32_e32 v126, s31, v11
	v_or_b32_e32 v128, s34, v11
	v_or_b32_e32 v129, s35, v10
	v_lshlrev_b64 v[120:121], 13, v[102:103]
	v_add_u32_e32 v102, s0, v127
	v_mov_b32_e32 v105, v103
	v_mov_b32_e32 v107, v103
	v_mov_b32_e32 v109, v103
	s_add_i32 s39, s30, 16
	v_add_u32_e32 v104, s23, v101
	v_or_b32_e32 v130, s36, v11
	v_or_b32_e32 v131, s37, v10
	v_or_b32_e32 v132, s38, v11
	v_or_b32_e32 v134, s40, v11
	v_or_b32_e32 v137, s42, v11
	v_or_b32_e32 v139, s27, v11
	v_add_u32_e32 v106, s23, v126
	v_add_u32_e32 v108, s23, v128
	v_lshlrev_b64 v[122:123], 13, v[102:103]
	v_add_u32_e32 v102, s0, v129
	v_mov_b32_e32 v111, v103
	v_mov_b32_e32 v113, v103
	v_mov_b32_e32 v115, v103
	v_mov_b32_e32 v117, v103
	v_mov_b32_e32 v119, v103
	s_add_i32 s41, s30, 20
	v_or_b32_e32 v133, s39, v10
	v_lshlrev_b64 v[104:105], 13, v[104:105]
	v_add_u32_e32 v110, s23, v130
	v_add_u32_e32 v112, s23, v132
	v_add_u32_e32 v114, s23, v134
	v_add_u32_e32 v116, s23, v137
	v_add_u32_e32 v118, s23, v139
	v_lshl_add_u64 v[120:121], v[2:3], 0, v[120:121]
	v_lshlrev_b64 v[106:107], 13, v[106:107]
	v_lshlrev_b64 v[108:109], 13, v[108:109]
	v_lshlrev_b64 v[124:125], 13, v[102:103]
	v_add_u32_e32 v102, s0, v131
	s_add_i32 s43, s30, 24
	v_or_b32_e32 v135, s41, v10
	v_lshl_add_u64 v[104:105], v[2:3], 0, v[104:105]
	v_lshlrev_b64 v[110:111], 13, v[110:111]
	v_lshlrev_b64 v[112:113], 13, v[112:113]
	v_lshlrev_b64 v[114:115], 13, v[114:115]
	v_lshlrev_b64 v[116:117], 13, v[116:117]
	v_lshlrev_b64 v[118:119], 13, v[118:119]
	v_lshl_add_u64 v[122:123], v[2:3], 0, v[122:123]
	v_lshl_add_u64 v[106:107], v[2:3], 0, v[106:107]
	v_lshl_add_u64 v[108:109], v[2:3], 0, v[108:109]
	global_load_dword v141, v[120:121], off nt
	global_load_dword v142, v[104:105], off nt
	v_lshlrev_b64 v[120:121], 13, v[102:103]
	v_add_u32_e32 v102, s0, v133
	s_add_i32 s30, s30, 28
	v_or_b32_e32 v138, s43, v10
	v_lshl_add_u64 v[110:111], v[2:3], 0, v[110:111]
	v_lshl_add_u64 v[112:113], v[2:3], 0, v[112:113]
	v_lshl_add_u64 v[114:115], v[2:3], 0, v[114:115]
	v_lshl_add_u64 v[116:117], v[2:3], 0, v[116:117]
	v_lshl_add_u64 v[118:119], v[2:3], 0, v[118:119]
	global_load_dword v143, v[122:123], off nt
	global_load_dword v144, v[106:107], off nt
	global_load_dword v145, v[108:109], off nt
	global_load_dword v146, v[110:111], off nt
	global_load_dword v147, v[112:113], off nt
	global_load_dword v148, v[114:115], off nt
	global_load_dword v149, v[116:117], off nt
	global_load_dword v150, v[118:119], off nt
	v_lshl_add_u64 v[106:107], v[2:3], 0, v[120:121]
	v_lshlrev_b64 v[108:109], 13, v[102:103]
	v_add_u32_e32 v102, s0, v135
	v_or_b32_e32 v140, s30, v10
	v_lshl_add_u64 v[104:105], v[2:3], 0, v[124:125]
	global_load_dword v151, v[106:107], off nt
	global_load_dword v152, v[104:105], off nt
	v_lshlrev_b64 v[106:107], 13, v[102:103]
	v_add_u32_e32 v102, s0, v138
	v_lshl_add_u64 v[104:105], v[2:3], 0, v[108:109]
	v_lshlrev_b64 v[108:109], 13, v[102:103]
	v_add_u32_e32 v102, s0, v140
	v_lshlrev_b64 v[110:111], 13, v[102:103]
	v_lshl_add_u64 v[110:111], v[2:3], 0, v[110:111]
	v_lshl_add_u64 v[106:107], v[2:3], 0, v[106:107]
	v_lshl_add_u64 v[108:109], v[2:3], 0, v[108:109]
	global_load_dword v102, v[110:111], off nt
	global_load_dword v153, v[108:109], off nt
	global_load_dword v154, v[106:107], off nt
	global_load_dword v155, v[104:105], off nt
	s_add_i32 s25, s25, 16
	s_add_i32 s24, s24, 16
	s_add_i32 s26, s26, -16
	s_cmp_lg_u32 s26, 0
	s_lshl_b32 s30, s25, 1
	s_lshl_b32 s27, s24, 1
	v_or_b32_e32 v45, s30, v10
	s_add_i32 s33, s30, 4
	s_add_i32 s31, s27, 4
	s_add_i32 s34, s27, 8
	s_add_i32 s35, s30, 8
	v_add_u32_e32 v0, s0, v45
	v_or_b32_e32 v63, s33, v10
	v_or_b32_e32 v39, s27, v11
	s_add_i32 s36, s27, 12
	s_add_i32 s37, s30, 12
	s_add_i32 s38, s27, 16
	s_add_i32 s40, s27, 20
	s_add_i32 s42, s27, 24
	s_add_i32 s27, s27, 28
	v_or_b32_e32 v62, s31, v11
	v_or_b32_e32 v64, s34, v11
	v_or_b32_e32 v65, s35, v10
	v_lshlrev_b64 v[56:57], 13, v[0:1]
	v_add_u32_e32 v0, s0, v63
	v_mov_b32_e32 v5, v1
	v_mov_b32_e32 v7, v1
	v_mov_b32_e32 v9, v1
	s_add_i32 s39, s30, 16
	v_add_u32_e32 v4, s23, v39
	v_or_b32_e32 v66, s36, v11
	v_or_b32_e32 v67, s37, v10
	v_or_b32_e32 v68, s38, v11
	v_or_b32_e32 v70, s40, v11
	v_or_b32_e32 v72, s42, v11
	v_or_b32_e32 v74, s27, v11
	v_add_u32_e32 v6, s23, v62
	v_add_u32_e32 v8, s23, v64
	v_lshlrev_b64 v[58:59], 13, v[0:1]
	v_add_u32_e32 v0, s0, v65
	v_mov_b32_e32 v47, v1
	v_mov_b32_e32 v49, v1
	v_mov_b32_e32 v51, v1
	v_mov_b32_e32 v53, v1
	v_mov_b32_e32 v55, v1
	s_add_i32 s41, s30, 20
	v_or_b32_e32 v69, s39, v10
	v_lshlrev_b64 v[4:5], 13, v[4:5]
	v_add_u32_e32 v46, s23, v66
	v_add_u32_e32 v48, s23, v68
	v_add_u32_e32 v50, s23, v70
	v_add_u32_e32 v52, s23, v72
	v_add_u32_e32 v54, s23, v74
	v_lshl_add_u64 v[56:57], v[2:3], 0, v[56:57]
	v_lshlrev_b64 v[6:7], 13, v[6:7]
	v_lshlrev_b64 v[8:9], 13, v[8:9]
	v_lshlrev_b64 v[60:61], 13, v[0:1]
	v_add_u32_e32 v0, s0, v67
	s_add_i32 s43, s30, 24
	v_or_b32_e32 v71, s41, v10
	v_lshl_add_u64 v[4:5], v[2:3], 0, v[4:5]
	v_lshlrev_b64 v[46:47], 13, v[46:47]
	v_lshlrev_b64 v[48:49], 13, v[48:49]
	v_lshlrev_b64 v[50:51], 13, v[50:51]
	v_lshlrev_b64 v[52:53], 13, v[52:53]
	v_lshlrev_b64 v[54:55], 13, v[54:55]
	v_lshl_add_u64 v[58:59], v[2:3], 0, v[58:59]
; #define GAS __attribute__((address_space(1)))
; #define LAS __attribute__((address_space(3)))
; #define LDS_WAIT() asm volatile("s_waitcnt lgkmcnt(0)" ::: "memory")
; __device__ __forceinline__ unsigned pk2(float lo, float hi) { unsigned r; asm("v_cvt_pk_bf16_f32 %0, %1, %2" : "=v"(r) : "v"(lo), "v"(hi)); return r; }
; __device__ __forceinline__ void cvt_item(gfp W, int N, bf16* WT, int Kd, int k0, int n0, int drow0, LAS float* scr, int lane, gfp gk) {
;     ...
;     for (int i = 0; i < 32; ++i) { const int kk = 2 * i + (lane >> 5); scr[kk * 33 + (lane & 31)] = W[(size_t)(k0 + kk) * N + n0 + (lane & 31)]; }
;     const int c = lane & 7;
;     f32x4 ga = (f32x4){1.f, 1.f, 1.f, 1.f}, gb = ga;
;     if (gk != nullptr) { ga = *(const GAS f32x4*)(gk + k0 + 8 * c); gb = *(const GAS f32x4*)(gk + k0 + 8 * c + 4); }
;     LDS_WAIT(); asm volatile("" ::: "memory");
; #pragma unroll
;     for (int j = 0; j < 4; ++j) { const int n = (lane >> 3) + 8 * j; const LAS float* s = scr + (8 * c) * 33 + n;
;         v4u o; o.x = pk2(s[0 * 33] * ga[0], s[1 * 33] * ga[1]); o.y = pk2(s[2 * 33] * ga[2], s[3 * 33] * ga[3]); o.z = pk2(s[4 * 33] * gb[0], s[5 * 33] * gb[1]); o.w = pk2(s[6 * 33] * gb[2], s[7 * 33] * gb[3]);
;         *(GAS v4u*)(WT + (size_t)(drow0 + n) * Kd + k0 + 8 * c) = o; }
;     LDS_WAIT(); asm volatile("" ::: "memory");
	v_lshl_add_u64 v[6:7], v[2:3], 0, v[6:7]
	v_lshl_add_u64 v[8:9], v[2:3], 0, v[8:9]
	global_load_dword v76, v[56:57], off nt
	global_load_dword v77, v[4:5], off nt
	v_lshlrev_b64 v[56:57], 13, v[0:1]
	v_add_u32_e32 v0, s0, v69
	s_add_i32 s30, s30, 28
	v_or_b32_e32 v73, s43, v10
	v_lshl_add_u64 v[46:47], v[2:3], 0, v[46:47]
	v_lshl_add_u64 v[48:49], v[2:3], 0, v[48:49]
	v_lshl_add_u64 v[50:51], v[2:3], 0, v[50:51]
	v_lshl_add_u64 v[52:53], v[2:3], 0, v[52:53]
	v_lshl_add_u64 v[54:55], v[2:3], 0, v[54:55]
	global_load_dword v78, v[58:59], off nt
	global_load_dword v79, v[6:7], off nt
	global_load_dword v80, v[8:9], off nt
	global_load_dword v81, v[46:47], off nt
	global_load_dword v82, v[48:49], off nt
	global_load_dword v83, v[50:51], off nt
	global_load_dword v84, v[52:53], off nt
	global_load_dword v85, v[54:55], off nt
	v_lshl_add_u64 v[6:7], v[2:3], 0, v[56:57]
	v_lshlrev_b64 v[8:9], 13, v[0:1]
	v_add_u32_e32 v0, s0, v71
	v_or_b32_e32 v75, s30, v10
	v_lshl_add_u64 v[4:5], v[2:3], 0, v[60:61]
	global_load_dword v86, v[6:7], off nt
	global_load_dword v87, v[4:5], off nt
	v_lshlrev_b64 v[6:7], 13, v[0:1]
	v_add_u32_e32 v0, s0, v73
	v_lshl_add_u64 v[4:5], v[2:3], 0, v[8:9]
	v_lshlrev_b64 v[8:9], 13, v[0:1]
	v_add_u32_e32 v0, s0, v75
	v_lshlrev_b64 v[46:47], 13, v[0:1]
	v_lshl_add_u64 v[46:47], v[2:3], 0, v[46:47]
	v_lshl_add_u64 v[6:7], v[2:3], 0, v[6:7]
	v_lshl_add_u64 v[8:9], v[2:3], 0, v[8:9]
	global_load_dword v0, v[46:47], off nt
	global_load_dword v88, v[8:9], off nt
	global_load_dword v89, v[6:7], off nt
	global_load_dword v90, v[4:5], off nt
	v_mad_u64_u32 v[104:105], s[30:31], v136, s81, v[12:13]
	v_mad_u64_u32 v[106:107], s[30:31], v101, s81, v[12:13]
	v_mad_u64_u32 v[108:109], s[30:31], v127, s81, v[12:13]
	v_mad_u64_u32 v[110:111], s[30:31], v126, s81, v[12:13]
	v_mad_u64_u32 v[112:113], s[30:31], v129, s81, v[12:13]
	v_mad_u64_u32 v[114:115], s[30:31], v128, s81, v[12:13]
	v_mad_u64_u32 v[116:117], s[30:31], v131, s81, v[12:13]
	v_mad_u64_u32 v[118:119], s[30:31], v130, s81, v[12:13]
	v_mad_u64_u32 v[120:121], s[30:31], v133, s81, v[12:13]
	v_mad_u64_u32 v[122:123], s[30:31], v132, s81, v[12:13]
	v_mad_u64_u32 v[124:125], s[30:31], v135, s81, v[12:13]
	v_mad_u64_u32 v[126:127], s[30:31], v134, s81, v[12:13]
	v_mad_u64_u32 v[128:129], s[30:31], v138, s81, v[12:13]
	v_mad_u64_u32 v[130:131], s[30:31], v137, s81, v[12:13]
	v_mad_u64_u32 v[132:133], s[30:31], v140, s81, v[12:13]
	v_mad_u64_u32 v[134:135], s[30:31], v139, s81, v[12:13]
	s_waitcnt vmcnt(31)
	ds_write_b32 v104, v141
	s_waitcnt vmcnt(30)
	ds_write_b32 v106, v142
	s_waitcnt vmcnt(29)
	ds_write_b32 v108, v143
	s_waitcnt vmcnt(28)
	ds_write_b32 v110, v144
	s_waitcnt vmcnt(20)
	ds_write_b32 v112, v152
	ds_write_b32 v114, v145
	ds_write_b32 v116, v151
	ds_write_b32 v118, v146
	s_waitcnt vmcnt(16)
	ds_write_b32 v120, v155
	ds_write_b32 v122, v147
	ds_write_b32 v124, v154
	ds_write_b32 v126, v148
	ds_write_b32 v128, v153
	ds_write_b32 v130, v149
	ds_write_b32 v132, v102
	ds_write_b32 v134, v150
	v_mad_u64_u32 v[4:5], s[30:31], v45, s81, v[12:13]
	v_mad_u64_u32 v[6:7], s[30:31], v39, s81, v[12:13]
	v_mad_u64_u32 v[8:9], s[30:31], v63, s81, v[12:13]
	v_mad_u64_u32 v[46:47], s[30:31], v62, s81, v[12:13]
	v_mad_u64_u32 v[48:49], s[30:31], v65, s81, v[12:13]
	v_mad_u64_u32 v[50:51], s[30:31], v64, s81, v[12:13]
	v_mad_u64_u32 v[52:53], s[30:31], v67, s81, v[12:13]
	v_mad_u64_u32 v[54:55], s[30:31], v66, s81, v[12:13]
	v_mad_u64_u32 v[56:57], s[30:31], v69, s81, v[12:13]
	v_mad_u64_u32 v[58:59], s[30:31], v68, s81, v[12:13]
	v_mad_u64_u32 v[60:61], s[30:31], v71, s81, v[12:13]
	v_mad_u64_u32 v[62:63], s[30:31], v70, s81, v[12:13]
	v_mad_u64_u32 v[64:65], s[30:31], v73, s81, v[12:13]
	v_mad_u64_u32 v[66:67], s[30:31], v72, s81, v[12:13]
	v_mad_u64_u32 v[68:69], s[30:31], v75, s81, v[12:13]
	v_mad_u64_u32 v[70:71], s[30:31], v74, s81, v[12:13]
	s_waitcnt vmcnt(15)
	ds_write_b32 v4, v76
	s_waitcnt vmcnt(14)
	ds_write_b32 v6, v77
	s_waitcnt vmcnt(13)
	ds_write_b32 v8, v78
	s_waitcnt vmcnt(12)
	ds_write_b32 v46, v79
	s_waitcnt vmcnt(4)
	ds_write_b32 v48, v87
	ds_write_b32 v50, v80
	ds_write_b32 v52, v86
	ds_write_b32 v54, v81
	s_waitcnt vmcnt(0)
	ds_write_b32 v56, v90
	ds_write_b32 v58, v82
	ds_write_b32 v60, v89
	ds_write_b32 v62, v83
	ds_write_b32 v64, v88
	ds_write_b32 v66, v84
	ds_write_b32 v68, v0
	ds_write_b32 v70, v85
	s_add_i32 s25, s25, 16
	s_add_i32 s24, s24, 16
	s_add_i32 s26, s26, -16
	s_cmp_lg_u32 s26, 0
	s_and_b32 s22, 0xffff, s22
	s_waitcnt lgkmcnt(0)
	v_or_b32_e32 v0, s22, v40
	s_lshl_b32 s0, s0, 1
	ds_read2_b32 v[6:7], v41 offset0:33 offset1:41
	ds_read2_b32 v[8:9], v41 offset1:8
	ds_read2_b32 v[46:47], v41 offset0:66 offset1:74
	ds_read2_b32 v[48:49], v41 offset0:99 offset1:107
	ds_read2_b32 v[50:51], v41 offset0:132 offset1:140
	ds_read2_b32 v[52:53], v41 offset0:165 offset1:173
	ds_read2_b32 v[54:55], v41 offset0:198 offset1:206
	ds_read2_b32 v[56:57], v41 offset0:231 offset1:239
	v_mul_u32_u24_e32 v0, 0x1600, v0
	v_lshl_add_u64 v[58:59], v[26:27], 0, s[0:1]
	v_lshlrev_b32_e32 v0, 1, v0
	v_lshl_add_u64 v[60:61], v[58:59], 0, v[0:1]
	v_or_b32_e32 v0, s22, v42
	v_mul_u32_u24_e32 v0, 0x1600, v0
	s_waitcnt lgkmcnt(6)
	v_cvt_pk_bf16_f32 v2, v8, v6
	v_lshlrev_b32_e32 v0, 1, v0
	s_waitcnt lgkmcnt(4)
	v_cvt_pk_bf16_f32 v3, v46, v48
	s_waitcnt lgkmcnt(2)
	v_cvt_pk_bf16_f32 v4, v50, v52
	s_waitcnt lgkmcnt(0)
	v_cvt_pk_bf16_f32 v5, v54, v56
	global_store_dwordx4 v[60:61], v[2:5], off nt
	s_nop 1
	v_cvt_pk_bf16_f32 v2, v9, v7
	v_lshl_add_u64 v[6:7], v[58:59], 0, v[0:1]
	v_or_b32_e32 v0, s22, v43
	v_cvt_pk_bf16_f32 v3, v47, v49
	v_cvt_pk_bf16_f32 v4, v51, v53
	v_cvt_pk_bf16_f32 v5, v55, v57
	ds_read2_b32 v[8:9], v41 offset0:16 offset1:24
	ds_read2_b32 v[46:47], v41 offset0:49 offset1:57
	ds_read2_b32 v[48:49], v41 offset0:82 offset1:90
	ds_read2_b32 v[50:51], v41 offset0:115 offset1:123
	ds_read2_b32 v[52:53], v41 offset0:148 offset1:156
	ds_read2_b32 v[54:55], v41 offset0:181 offset1:189
	ds_read2_b32 v[56:57], v41 offset0:214 offset1:222
	ds_read2_b32 v[60:61], v41 offset0:247 offset1:255
	v_mul_u32_u24_e32 v0, 0x1600, v0
	v_lshlrev_b32_e32 v0, 1, v0
	global_store_dwordx4 v[6:7], v[2:5], off nt
	v_lshl_add_u64 v[6:7], v[58:59], 0, v[0:1]
	v_or_b32_e32 v0, s22, v44
	v_mul_u32_u24_e32 v0, 0x1600, v0
	v_lshlrev_b32_e32 v0, 1, v0
	s_waitcnt lgkmcnt(6)
	v_cvt_pk_bf16_f32 v2, v8, v46
	s_waitcnt lgkmcnt(4)
	v_cvt_pk_bf16_f32 v3, v48, v50
	s_waitcnt lgkmcnt(2)
	v_cvt_pk_bf16_f32 v4, v52, v54
	s_waitcnt lgkmcnt(0)
	v_cvt_pk_bf16_f32 v5, v56, v60
	global_store_dwordx4 v[6:7], v[2:5], off nt
	v_lshl_add_u64 v[6:7], v[58:59], 0, v[0:1]
	s_nop 0
	v_cvt_pk_bf16_f32 v2, v9, v47
	v_cvt_pk_bf16_f32 v3, v49, v51
	v_cvt_pk_bf16_f32 v4, v53, v55
	v_cvt_pk_bf16_f32 v5, v57, v61
	global_store_dwordx4 v[6:7], v[2:5], off nt
	s_waitcnt lgkmcnt(0)

; #define GAS __attribute__((address_space(1)))
; #define LAS __attribute__((address_space(3)))
; #define LDS_WAIT() asm volatile("s_waitcnt lgkmcnt(0)" ::: "memory")
; __device__ __forceinline__ unsigned pk2(float lo, float hi) { unsigned r; asm("v_cvt_pk_bf16_f32 %0, %1, %2" : "=v"(r) : "v"(lo), "v"(hi)); return r; }
; __device__ __forceinline__ void cvt_item(gfp W, int N, bf16* WT, int Kd, int k0, int n0, int drow0, LAS float* scr, int lane, gfp gk) {
;     ...
;     LDS_WAIT(); asm volatile("" ::: "memory");
; #pragma unroll
;     for (int j = 0; j < 4; ++j) { const int n = (lane >> 3) + 8 * j; const LAS float* s = scr + (8 * c) * 33 + n;
;         v4u o; o.x = pk2(s[0 * 33] * ga[0], s[1 * 33] * ga[1]); o.y = pk2(s[2 * 33] * ga[2], s[3 * 33] * ga[3]); o.z = pk2(s[4 * 33] * gb[0], s[5 * 33] * gb[1]); o.w = pk2(s[6 * 33] * gb[2], s[7 * 33] * gb[3]);
;         *(GAS v4u*)(WT + (size_t)(drow0 + n) * Kd + k0 + 8 * c) = o; }
;     LDS_WAIT(); asm volatile("" ::: "memory");
; __device__ __forceinline__ void cvt_gu(gfp W, bf16* WT, int half, int item, LAS float* scr, int lane, gfp gk) {
;     const int nblk = FF / 32, kb = item / nblk, nb = item % nblk, n0 = 32 * nb;
;     cvt_item(W, FF, WT, D, 64 * kb, n0, 256 * (n0 >> 7) + 128 * half + (n0 & 127), scr, lane, gk);
.LBB0_181:
	s_waitcnt lgkmcnt(0)
	ds_read2_b32 v[50:51], v41 offset1:8
	ds_read2_b32 v[52:53], v41 offset0:33 offset1:41
	ds_read2_b32 v[56:57], v41 offset0:66 offset1:74
	ds_read2_b32 v[58:59], v41 offset0:99 offset1:107
	ds_read2_b32 v[60:61], v41 offset0:132 offset1:140
	ds_read2_b32 v[62:63], v41 offset0:165 offset1:173
	ds_read2_b32 v[64:65], v41 offset0:198 offset1:206
	ds_read2_b32 v[66:67], v41 offset0:231 offset1:239
	s_lshl_b32 s22, s24, 6
	s_waitcnt vmcnt(0) lgkmcnt(7)
	v_mul_f32_e32 v0, v6, v50
	s_and_b32 s22, s22, 0x3f00
	s_and_b32 s0, s0, 0x60
	s_waitcnt lgkmcnt(6)
	v_mul_f32_e32 v39, v7, v52
	v_cvt_pk_bf16_f32 v46, v0, v39
	s_waitcnt lgkmcnt(5)
	v_mul_f32_e32 v0, v8, v56
	s_or_b32 s0, s0, s22
	s_waitcnt lgkmcnt(4)
	v_mul_f32_e32 v39, v9, v58
	v_cvt_pk_bf16_f32 v47, v0, v39
	s_waitcnt lgkmcnt(3)
	v_mul_f32_e32 v0, v2, v60
	s_or_b32 s22, s0, 0x80
	s_waitcnt lgkmcnt(2)
	v_mul_f32_e32 v39, v3, v62
	v_cvt_pk_bf16_f32 v48, v0, v39
	s_waitcnt lgkmcnt(1)
	v_mul_f32_e32 v0, v4, v64
	s_lshl_b32 s0, s25, 1
	s_waitcnt lgkmcnt(0)
	v_mul_f32_e32 v39, v5, v66
	v_cvt_pk_bf16_f32 v49, v0, v39
	v_or_b32_e32 v0, s22, v40
	v_lshl_add_u64 v[54:55], v[34:35], 0, s[0:1]
	v_lshlrev_b32_e32 v0, 12, v0
	v_lshl_add_u64 v[68:69], v[54:55], 0, v[0:1]
	v_mul_f32_e32 v0, v6, v51
	global_store_dwordx4 v[68:69], v[46:49], off nt
	v_mul_f32_e32 v39, v7, v53
	s_nop 0
	v_cvt_pk_bf16_f32 v46, v0, v39
	v_mul_f32_e32 v0, v8, v57
	v_mul_f32_e32 v39, v9, v59
	v_cvt_pk_bf16_f32 v47, v0, v39
	v_mul_f32_e32 v0, v2, v61
	v_mul_f32_e32 v39, v3, v63
	v_cvt_pk_bf16_f32 v48, v0, v39
	v_mul_f32_e32 v0, v4, v65
	v_mul_f32_e32 v39, v5, v67
	v_cvt_pk_bf16_f32 v49, v0, v39
	v_or_b32_e32 v0, s22, v42
	v_lshlrev_b32_e32 v0, 12, v0
	v_lshl_add_u64 v[50:51], v[54:55], 0, v[0:1]
	ds_read2_b32 v[52:53], v41 offset0:16 offset1:24
	ds_read2_b32 v[56:57], v41 offset0:49 offset1:57
	global_store_dwordx4 v[50:51], v[46:49], off nt
	ds_read2_b32 v[50:51], v41 offset0:82 offset1:90
	ds_read2_b32 v[58:59], v41 offset0:115 offset1:123
	ds_read2_b32 v[60:61], v41 offset0:148 offset1:156
	ds_read2_b32 v[62:63], v41 offset0:181 offset1:189
	ds_read2_b32 v[64:65], v41 offset0:214 offset1:222
	ds_read2_b32 v[66:67], v41 offset0:247 offset1:255
	s_waitcnt lgkmcnt(7)
	v_mul_f32_e32 v0, v6, v52
	s_waitcnt lgkmcnt(6)
	v_mul_f32_e32 v39, v7, v56
	v_cvt_pk_bf16_f32 v46, v0, v39
	s_waitcnt lgkmcnt(5)
	v_mul_f32_e32 v0, v8, v50
	s_waitcnt lgkmcnt(4)
	v_mul_f32_e32 v39, v9, v58
	v_cvt_pk_bf16_f32 v47, v0, v39
	s_waitcnt lgkmcnt(3)
	v_mul_f32_e32 v0, v2, v60
	s_waitcnt lgkmcnt(2)
	v_mul_f32_e32 v39, v3, v62
	v_cvt_pk_bf16_f32 v48, v0, v39
	s_waitcnt lgkmcnt(1)
	v_mul_f32_e32 v0, v4, v64
	s_waitcnt lgkmcnt(0)
	v_mul_f32_e32 v39, v5, v66
	v_cvt_pk_bf16_f32 v49, v0, v39
	v_or_b32_e32 v0, s22, v43
	v_lshlrev_b32_e32 v0, 12, v0
	v_lshl_add_u64 v[68:69], v[54:55], 0, v[0:1]
	v_mul_f32_e32 v0, v6, v53
	v_mul_f32_e32 v6, v7, v57
	v_cvt_pk_bf16_f32 v6, v0, v6
	v_mul_f32_e32 v0, v8, v51
	v_mul_f32_e32 v7, v9, v59
	v_cvt_pk_bf16_f32 v7, v0, v7
	v_mul_f32_e32 v0, v2, v61
	v_mul_f32_e32 v2, v3, v63
	v_cvt_pk_bf16_f32 v8, v0, v2
	v_mul_f32_e32 v0, v4, v65
	v_mul_f32_e32 v2, v5, v67
	v_cvt_pk_bf16_f32 v9, v0, v2
	v_or_b32_e32 v0, s22, v44
	v_lshlrev_b32_e32 v0, 12, v0
	v_lshl_add_u64 v[2:3], v[54:55], 0, v[0:1]
	global_store_dwordx4 v[68:69], v[46:49], off nt
	global_store_dwordx4 v[2:3], v[6:9], off nt
	s_waitcnt lgkmcnt(0)

; #define GAS __attribute__((address_space(1)))
; #define LAS __attribute__((address_space(3)))
; #define LDS_WAIT() asm volatile("s_waitcnt lgkmcnt(0)" ::: "memory")
; __device__ __forceinline__ unsigned pk2(float lo, float hi) { unsigned r; asm("v_cvt_pk_bf16_f32 %0, %1, %2" : "=v"(r) : "v"(lo), "v"(hi)); return r; }
; __device__ __forceinline__ void cvt_item(gfp W, int N, bf16* WT, int Kd, int k0, int n0, int drow0, LAS float* scr, int lane, gfp gk) {
;     ...
;     LDS_WAIT(); asm volatile("" ::: "memory");
; #pragma unroll
;     for (int j = 0; j < 4; ++j) { const int n = (lane >> 3) + 8 * j; const LAS float* s = scr + (8 * c) * 33 + n;
;         v4u o; o.x = pk2(s[0 * 33] * ga[0], s[1 * 33] * ga[1]); o.y = pk2(s[2 * 33] * ga[2], s[3 * 33] * ga[3]); o.z = pk2(s[4 * 33] * gb[0], s[5 * 33] * gb[1]); o.w = pk2(s[6 * 33] * gb[2], s[7 * 33] * gb[3]);
;         *(GAS v4u*)(WT + (size_t)(drow0 + n) * Kd + k0 + 8 * c) = o; }
;     LDS_WAIT(); asm volatile("" ::: "memory");
; __device__ __forceinline__ void cvt_gu(gfp W, bf16* WT, int half, int item, LAS float* scr, int lane, gfp gk) {
;     const int nblk = FF / 32, kb = item / nblk, nb = item % nblk, n0 = 32 * nb;
;     cvt_item(W, FF, WT, D, 64 * kb, n0, 256 * (n0 >> 7) + 128 * half + (n0 & 127), scr, lane, gk);
.LBB0_189:
	s_waitcnt lgkmcnt(0)
	ds_read2_b32 v[50:51], v41 offset1:8
	ds_read2_b32 v[52:53], v41 offset0:33 offset1:41
	ds_read2_b32 v[56:57], v41 offset0:66 offset1:74
	ds_read2_b32 v[58:59], v41 offset0:99 offset1:107
	ds_read2_b32 v[60:61], v41 offset0:132 offset1:140
	ds_read2_b32 v[62:63], v41 offset0:165 offset1:173
	ds_read2_b32 v[64:65], v41 offset0:198 offset1:206
	ds_read2_b32 v[66:67], v41 offset0:231 offset1:239
	s_waitcnt vmcnt(0) lgkmcnt(7)
	v_mul_f32_e32 v0, v6, v50
	s_lshl_b32 s22, s24, 6
	s_waitcnt lgkmcnt(6)
	v_mul_f32_e32 v39, v7, v52
	v_cvt_pk_bf16_f32 v46, v0, v39
	s_waitcnt lgkmcnt(5)
	v_mul_f32_e32 v0, v8, v56
	s_and_b32 s22, s22, 0x3f00
	s_and_b32 s0, s0, 0x60
	s_waitcnt lgkmcnt(4)
	v_mul_f32_e32 v39, v9, v58
	v_cvt_pk_bf16_f32 v47, v0, v39
	s_waitcnt lgkmcnt(3)
	v_mul_f32_e32 v0, v2, v60
	s_or_b32 s22, s22, s0
	s_waitcnt lgkmcnt(2)
	v_mul_f32_e32 v39, v3, v62
	v_cvt_pk_bf16_f32 v48, v0, v39
	s_waitcnt lgkmcnt(1)
	v_mul_f32_e32 v0, v4, v64
	s_lshl_b32 s0, s25, 1
	s_waitcnt lgkmcnt(0)
	v_mul_f32_e32 v39, v5, v66
	v_cvt_pk_bf16_f32 v49, v0, v39
	v_or_b32_e32 v0, s22, v40
	v_lshl_add_u64 v[54:55], v[34:35], 0, s[0:1]
	v_lshlrev_b32_e32 v0, 12, v0
	v_lshl_add_u64 v[68:69], v[54:55], 0, v[0:1]
	v_mul_f32_e32 v0, v6, v51
	global_store_dwordx4 v[68:69], v[46:49], off nt
	v_mul_f32_e32 v39, v7, v53
	s_nop 0
	v_cvt_pk_bf16_f32 v46, v0, v39
	v_mul_f32_e32 v0, v8, v57
	v_mul_f32_e32 v39, v9, v59
	v_cvt_pk_bf16_f32 v47, v0, v39
	v_mul_f32_e32 v0, v2, v61
	v_mul_f32_e32 v39, v3, v63
	v_cvt_pk_bf16_f32 v48, v0, v39
	v_mul_f32_e32 v0, v4, v65
	v_mul_f32_e32 v39, v5, v67
	v_cvt_pk_bf16_f32 v49, v0, v39
	v_or_b32_e32 v0, s22, v42
	v_lshlrev_b32_e32 v0, 12, v0
	v_lshl_add_u64 v[50:51], v[54:55], 0, v[0:1]
	ds_read2_b32 v[52:53], v41 offset0:16 offset1:24
	ds_read2_b32 v[56:57], v41 offset0:49 offset1:57
	global_store_dwordx4 v[50:51], v[46:49], off nt
	ds_read2_b32 v[50:51], v41 offset0:82 offset1:90
	ds_read2_b32 v[58:59], v41 offset0:115 offset1:123
	ds_read2_b32 v[60:61], v41 offset0:148 offset1:156
	ds_read2_b32 v[62:63], v41 offset0:181 offset1:189
	ds_read2_b32 v[64:65], v41 offset0:214 offset1:222
	ds_read2_b32 v[66:67], v41 offset0:247 offset1:255
	s_waitcnt lgkmcnt(7)
	v_mul_f32_e32 v0, v6, v52
	s_waitcnt lgkmcnt(6)
	v_mul_f32_e32 v39, v7, v56
	v_cvt_pk_bf16_f32 v46, v0, v39
	s_waitcnt lgkmcnt(5)
	v_mul_f32_e32 v0, v8, v50
	s_waitcnt lgkmcnt(4)
	v_mul_f32_e32 v39, v9, v58
	v_cvt_pk_bf16_f32 v47, v0, v39
	s_waitcnt lgkmcnt(3)
	v_mul_f32_e32 v0, v2, v60
	s_waitcnt lgkmcnt(2)
	v_mul_f32_e32 v39, v3, v62
	v_cvt_pk_bf16_f32 v48, v0, v39
	s_waitcnt lgkmcnt(1)
	v_mul_f32_e32 v0, v4, v64
	s_waitcnt lgkmcnt(0)
	v_mul_f32_e32 v39, v5, v66
	v_cvt_pk_bf16_f32 v49, v0, v39
	v_or_b32_e32 v0, s22, v43
	v_lshlrev_b32_e32 v0, 12, v0
	v_lshl_add_u64 v[68:69], v[54:55], 0, v[0:1]
	v_mul_f32_e32 v0, v6, v53
	v_mul_f32_e32 v6, v7, v57
	v_cvt_pk_bf16_f32 v6, v0, v6
	v_mul_f32_e32 v0, v8, v51
	v_mul_f32_e32 v7, v9, v59
	v_cvt_pk_bf16_f32 v7, v0, v7
	v_mul_f32_e32 v0, v2, v61
	v_mul_f32_e32 v2, v3, v63
	v_cvt_pk_bf16_f32 v8, v0, v2
	v_mul_f32_e32 v0, v4, v65
	v_mul_f32_e32 v2, v5, v67
	v_cvt_pk_bf16_f32 v9, v0, v2
	v_or_b32_e32 v0, s22, v44
	v_lshlrev_b32_e32 v0, 12, v0
	v_lshl_add_u64 v[2:3], v[54:55], 0, v[0:1]
	global_store_dwordx4 v[68:69], v[46:49], off nt
	global_store_dwordx4 v[2:3], v[6:9], off nt
	s_waitcnt lgkmcnt(0)

; #define GAS __attribute__((address_space(1)))
; #define LAS __attribute__((address_space(3)))
; #define LDS_WAIT() asm volatile("s_waitcnt lgkmcnt(0)" ::: "memory")
; __device__ __forceinline__ unsigned pk2(float lo, float hi) { unsigned r; asm("v_cvt_pk_bf16_f32 %0, %1, %2" : "=v"(r) : "v"(lo), "v"(hi)); return r; }
; __device__ __forceinline__ void cvt_item(gfp W, int N, bf16* WT, int Kd, int k0, int n0, int drow0, LAS float* scr, int lane, gfp gk) {
;     ...
;     LDS_WAIT(); asm volatile("" ::: "memory");
; #pragma unroll
;     for (int j = 0; j < 4; ++j) { const int n = (lane >> 3) + 8 * j; const LAS float* s = scr + (8 * c) * 33 + n;
;         v4u o; o.x = pk2(s[0 * 33] * ga[0], s[1 * 33] * ga[1]); o.y = pk2(s[2 * 33] * ga[2], s[3 * 33] * ga[3]); o.z = pk2(s[4 * 33] * gb[0], s[5 * 33] * gb[1]); o.w = pk2(s[6 * 33] * gb[2], s[7 * 33] * gb[3]);
;         *(GAS v4u*)(WT + (size_t)(drow0 + n) * Kd + k0 + 8 * c) = o; }
;     LDS_WAIT(); asm volatile("" ::: "memory");
; __device__ __forceinline__ void cvt_gu(gfp W, bf16* WT, int half, int item, LAS float* scr, int lane, gfp gk) {
;     const int nblk = FF / 32, kb = item / nblk, nb = item % nblk, n0 = 32 * nb;
;     cvt_item(W, FF, WT, D, 64 * kb, n0, 256 * (n0 >> 7) + 128 * half + (n0 & 127), scr, lane, gk);
.LBB0_197:
	s_waitcnt lgkmcnt(0)
	ds_read2_b32 v[50:51], v41 offset1:8
	ds_read2_b32 v[52:53], v41 offset0:33 offset1:41
	ds_read2_b32 v[56:57], v41 offset0:66 offset1:74
	ds_read2_b32 v[58:59], v41 offset0:99 offset1:107
	ds_read2_b32 v[60:61], v41 offset0:132 offset1:140
	ds_read2_b32 v[62:63], v41 offset0:165 offset1:173
	ds_read2_b32 v[64:65], v41 offset0:198 offset1:206
	ds_read2_b32 v[66:67], v41 offset0:231 offset1:239
	s_lshl_b32 s22, s24, 6
	s_waitcnt vmcnt(0) lgkmcnt(7)
	v_mul_f32_e32 v0, v6, v50
	s_and_b32 s22, s22, 0x3f00
	s_and_b32 s0, s0, 0x60
	s_waitcnt lgkmcnt(6)
	v_mul_f32_e32 v39, v7, v52
	v_cvt_pk_bf16_f32 v46, v0, v39
	s_waitcnt lgkmcnt(5)
	v_mul_f32_e32 v0, v8, v56
	s_or_b32 s0, s0, s22
	s_waitcnt lgkmcnt(4)
	v_mul_f32_e32 v39, v9, v58
	v_cvt_pk_bf16_f32 v47, v0, v39
	s_waitcnt lgkmcnt(3)
	v_mul_f32_e32 v0, v2, v60
	s_or_b32 s22, s0, 0x80
	s_waitcnt lgkmcnt(2)
	v_mul_f32_e32 v39, v3, v62
	v_cvt_pk_bf16_f32 v48, v0, v39
	s_waitcnt lgkmcnt(1)
	v_mul_f32_e32 v0, v4, v64
	s_lshl_b32 s0, s25, 1
	s_waitcnt lgkmcnt(0)
	v_mul_f32_e32 v39, v5, v66
	v_cvt_pk_bf16_f32 v49, v0, v39
	v_or_b32_e32 v0, s22, v40
	v_lshl_add_u64 v[54:55], v[36:37], 0, s[0:1]
	v_lshlrev_b32_e32 v0, 12, v0
	v_lshl_add_u64 v[68:69], v[54:55], 0, v[0:1]
	v_mul_f32_e32 v0, v6, v51
	global_store_dwordx4 v[68:69], v[46:49], off nt
	v_mul_f32_e32 v39, v7, v53
	s_nop 0
	v_cvt_pk_bf16_f32 v46, v0, v39
	v_mul_f32_e32 v0, v8, v57
	v_mul_f32_e32 v39, v9, v59
	v_cvt_pk_bf16_f32 v47, v0, v39
	v_mul_f32_e32 v0, v2, v61
	v_mul_f32_e32 v39, v3, v63
	v_cvt_pk_bf16_f32 v48, v0, v39
	v_mul_f32_e32 v0, v4, v65
	v_mul_f32_e32 v39, v5, v67
	v_cvt_pk_bf16_f32 v49, v0, v39
	v_or_b32_e32 v0, s22, v42
	v_lshlrev_b32_e32 v0, 12, v0
	v_lshl_add_u64 v[50:51], v[54:55], 0, v[0:1]
	ds_read2_b32 v[52:53], v41 offset0:16 offset1:24
	ds_read2_b32 v[56:57], v41 offset0:49 offset1:57
	global_store_dwordx4 v[50:51], v[46:49], off nt
	ds_read2_b32 v[50:51], v41 offset0:82 offset1:90
	ds_read2_b32 v[58:59], v41 offset0:115 offset1:123
	ds_read2_b32 v[60:61], v41 offset0:148 offset1:156
	ds_read2_b32 v[62:63], v41 offset0:181 offset1:189
	ds_read2_b32 v[64:65], v41 offset0:214 offset1:222
	ds_read2_b32 v[66:67], v41 offset0:247 offset1:255
	s_waitcnt lgkmcnt(7)
	v_mul_f32_e32 v0, v6, v52
	s_waitcnt lgkmcnt(6)
	v_mul_f32_e32 v39, v7, v56
	v_cvt_pk_bf16_f32 v46, v0, v39
	s_waitcnt lgkmcnt(5)
	v_mul_f32_e32 v0, v8, v50
	s_waitcnt lgkmcnt(4)
	v_mul_f32_e32 v39, v9, v58
	v_cvt_pk_bf16_f32 v47, v0, v39
	s_waitcnt lgkmcnt(3)
	v_mul_f32_e32 v0, v2, v60
	s_waitcnt lgkmcnt(2)
	v_mul_f32_e32 v39, v3, v62
	v_cvt_pk_bf16_f32 v48, v0, v39
	s_waitcnt lgkmcnt(1)
	v_mul_f32_e32 v0, v4, v64
	s_waitcnt lgkmcnt(0)
	v_mul_f32_e32 v39, v5, v66
	v_cvt_pk_bf16_f32 v49, v0, v39
	v_or_b32_e32 v0, s22, v43
	v_lshlrev_b32_e32 v0, 12, v0
	v_lshl_add_u64 v[68:69], v[54:55], 0, v[0:1]
	v_mul_f32_e32 v0, v6, v53
	v_mul_f32_e32 v6, v7, v57
	v_cvt_pk_bf16_f32 v6, v0, v6
	v_mul_f32_e32 v0, v8, v51
	v_mul_f32_e32 v7, v9, v59
	v_cvt_pk_bf16_f32 v7, v0, v7
	v_mul_f32_e32 v0, v2, v61
	v_mul_f32_e32 v2, v3, v63
	v_cvt_pk_bf16_f32 v8, v0, v2
	v_mul_f32_e32 v0, v4, v65
	v_mul_f32_e32 v2, v5, v67
	v_cvt_pk_bf16_f32 v9, v0, v2
	v_or_b32_e32 v0, s22, v44
	v_lshlrev_b32_e32 v0, 12, v0
	v_lshl_add_u64 v[2:3], v[54:55], 0, v[0:1]
	global_store_dwordx4 v[68:69], v[46:49], off nt
	global_store_dwordx4 v[2:3], v[6:9], off nt
	s_waitcnt lgkmcnt(0)
